# accumulator zeroing moved from the per-tile critical path into the store-bound epilogue for in_proj and ff13 GEMMs (plus saddr LDS-DMA in all K-loops)
# baseline (speedup 1.0000x reference)
; #define PG8_STAGE(bufoff, gbase, voff) do { _Pragma("unroll") for (int _i = 0; _i < 2; ++_i) \
;         __builtin_amdgcn_global_load_lds((const unsigned*)((const char*)(gbase) + (voff)[_i]), (LAS unsigned*)(lds + (bufoff) + ldsw + _i * 8192), 16, 0, 0); } while (0)
; #define PG8_LDA(dst, b, h) do { _Pragma("unroll") for (int m = 0; m < 4; ++m) _Pragma("unroll") for (int k = 0; k < 2; ++k) dst[m][k] = *(const LAS bf16x8*)(lds + PG8_SA(b, h) + aoff + m * 2048 + k * 1024); } while (0)
; #define PG8_LDB(dst, b, h) do { _Pragma("unroll") for (int n = 0; n < 2; ++n) _Pragma("unroll") for (int k = 0; k < 2; ++k) dst[n][k] = *(const LAS bf16x8*)(lds + PG8_SB(b, h) + boff + n * 2048 + k * 1024); } while (0)
; #define PG8_MMA(ai, bj, At, Bt) do { __builtin_amdgcn_s_setprio(1); _Pragma("unroll") for (int m = 0; m < 4; ++m) _Pragma("unroll") for (int n = 0; n < 2; ++n) _Pragma("unroll") for (int k = 0; k < 2; ++k) \
;         acc[ai][bj][m][n] = __builtin_amdgcn_mfma_f32_16x16x32_bf16(Bt[n][k], At[m][k], acc[ai][bj][m][n], 0, 0, 0); __builtin_amdgcn_s_setprio(0); } while (0)
; #define PG8_WAIT_L(n) asm volatile("s_waitcnt lgkmcnt(" #n ")" ::: "memory")
; #define PG8_BAR __builtin_amdgcn_s_barrier()
; #define PG8_SCHED __builtin_amdgcn_sched_barrier(0)
; template <class Epi>
; __device__ __forceinline__ void gemm_phase(LAS unsigned char* lds, const Gemm g, const StaticOrder& S, const Epi& E) {
;     ...
;         for (int t = 0; t < nt; t += 2) {
;             const bool last = (t == nt - 2);
;             const char* a1 = cA + (size_t)(t + 1) * kstep;
;             const char* a2 = last ? nA : cA + (size_t)(t + 2) * kstep; const char* b2 = last ? nB : cB + (size_t)(t + 2) * kstep;
;             const char* a3 = a2 + kstep; const char* b3 = b2 + kstep;
;             PG8_LDB(B0, 0, 0); PG8_SCHED; PG8_LDA(At, 0, 0); PG8_STAGE(PG8_SA(1, 1), a1 + hA, voffA);
;             PG8_WAIT_L(8); PG8_BAR; PG8_WAIT_L(0); PG8_MMA(0, 0, At, B0); PG8_BAR; PG8_SCHED;
;     ...
;         if (!(Epi::PAIRS && cur.alt == 0)) {
; #pragma unroll
;         for (int a = 0; a < 2; ++a)
; #pragma unroll
;             for (int b = 0; b < 2; ++b)
; #pragma unroll
;                 for (int m = 0; m < 4; ++m)
; #pragma unroll
;                     for (int n = 0; n < 2; ++n) acc[a][b][m][n] = (f32x4){0.f, 0.f, 0.f, 0.f}; }
.LBB0_103:
	s_ashr_i32 s43, s42, 31
	v_mov_b64_e32 v[2:3], 0xb16
	s_lshl_b64 s[22:23], s[42:43], 19
	v_cmp_lt_i64_e32 vcc, s[44:45], v[2:3]
	s_add_u32 s44, s36, s22
	s_addc_u32 s45, s37, s23
	s_and_b64 s[22:23], vcc, exec
	s_cselect_b32 s43, s45, s63
	s_cselect_b32 s61, s44, s62
	s_ashr_i32 s41, s40, 31
	s_lshl_b64 s[22:23], s[40:41], 19
	s_add_u32 s58, s29, s22
	s_addc_u32 s59, s9, s23
	s_and_b64 s[22:23], vcc, exec
	s_cselect_b32 s41, s59, s65
	s_cselect_b32 s69, s58, s64
	s_add_u32 s62, s62, 0x40080
	s_addc_u32 s63, s63, 0
	s_add_u32 s70, s64, 0x100
	v_mov_b32_e32 v2, 0
	s_addc_u32 s71, s65, 0
	s_mov_b32 s74, -2
	s_cmp_eq_u32 s68, 1
	s_cbranch_scc1 .Lzf_s9
	v_mov_b32_e32 v3, v2
	v_mov_b32_e32 v4, v2
	v_mov_b32_e32 v5, v2
	v_mov_b32_e32 v6, v2
	s_branch .LBB0_104
.Lzf_s9:
	v_mov_b32_e32 v3, v2
	v_mov_b32_e32 v4, v2
	v_mov_b32_e32 v5, v2
	v_mov_b32_e32 v10, v2
	v_mov_b32_e32 v11, v2
	v_mov_b32_e32 v12, v2
	v_mov_b32_e32 v13, v2
	v_mov_b32_e32 v18, v2
	v_mov_b32_e32 v19, v2
	v_mov_b32_e32 v20, v2
	v_mov_b32_e32 v21, v2
	v_mov_b32_e32 v26, v2
	v_mov_b32_e32 v27, v2
	v_mov_b32_e32 v28, v2
	v_mov_b32_e32 v29, v2
	v_mov_b32_e32 v34, v2
	v_mov_b32_e32 v35, v2
	v_mov_b32_e32 v36, v2
	v_mov_b32_e32 v37, v2
	v_mov_b32_e32 v42, v2
	v_mov_b32_e32 v43, v2
	v_mov_b32_e32 v44, v2
	v_mov_b32_e32 v45, v2
	v_mov_b32_e32 v50, v2
	v_mov_b32_e32 v51, v2
	v_mov_b32_e32 v52, v2
	v_mov_b32_e32 v53, v2
	v_mov_b32_e32 v58, v2
	v_mov_b32_e32 v59, v2
	v_mov_b32_e32 v60, v2
	v_mov_b32_e32 v61, v2
	v_mov_b32_e32 v6, v2
	v_mov_b32_e32 v7, v2
	v_mov_b32_e32 v8, v2
	v_mov_b32_e32 v9, v2
	v_mov_b32_e32 v14, v2
	v_mov_b32_e32 v15, v2
	v_mov_b32_e32 v16, v2
	v_mov_b32_e32 v17, v2
	v_mov_b32_e32 v22, v2
	v_mov_b32_e32 v23, v2
	v_mov_b32_e32 v24, v2
	v_mov_b32_e32 v25, v2
	v_mov_b32_e32 v30, v2
	v_mov_b32_e32 v31, v2
	v_mov_b32_e32 v32, v2
	v_mov_b32_e32 v33, v2
	v_mov_b32_e32 v38, v2
	v_mov_b32_e32 v39, v2
	v_mov_b32_e32 v40, v2
	v_mov_b32_e32 v41, v2
	v_mov_b32_e32 v46, v2
	v_mov_b32_e32 v47, v2
	v_mov_b32_e32 v48, v2
	v_mov_b32_e32 v49, v2
	v_mov_b32_e32 v54, v2
	v_mov_b32_e32 v55, v2
	v_mov_b32_e32 v56, v2
	v_mov_b32_e32 v57, v2
	v_mov_b32_e32 v62, v2
	v_mov_b32_e32 v63, v2
	v_mov_b32_e32 v64, v2
	v_mov_b32_e32 v65, v2
	v_mov_b32_e32 v66, v2
	v_mov_b32_e32 v67, v2
	v_mov_b32_e32 v68, v2
	v_mov_b32_e32 v69, v2
	v_mov_b32_e32 v74, v2
	v_mov_b32_e32 v75, v2
	v_mov_b32_e32 v76, v2
	v_mov_b32_e32 v77, v2
	v_mov_b32_e32 v82, v2
	v_mov_b32_e32 v83, v2
	v_mov_b32_e32 v84, v2
	v_mov_b32_e32 v85, v2
	v_mov_b32_e32 v90, v2
	v_mov_b32_e32 v91, v2
	v_mov_b32_e32 v92, v2
	v_mov_b32_e32 v93, v2
	v_mov_b32_e32 v98, v2
	v_mov_b32_e32 v99, v2
	v_mov_b32_e32 v100, v2
	v_mov_b32_e32 v101, v2
	v_mov_b32_e32 v106, v2
	v_mov_b32_e32 v107, v2
	v_mov_b32_e32 v108, v2
	v_mov_b32_e32 v109, v2
	v_mov_b32_e32 v114, v2
	v_mov_b32_e32 v115, v2
	v_mov_b32_e32 v116, v2
	v_mov_b32_e32 v117, v2
	v_mov_b32_e32 v122, v2
	v_mov_b32_e32 v123, v2
	v_mov_b32_e32 v124, v2
	v_mov_b32_e32 v125, v2
	v_mov_b32_e32 v70, v2
	v_mov_b32_e32 v71, v2
	v_mov_b32_e32 v72, v2
	v_mov_b32_e32 v73, v2
	v_mov_b32_e32 v78, v2
	v_mov_b32_e32 v79, v2
	v_mov_b32_e32 v80, v2
	v_mov_b32_e32 v81, v2
	v_mov_b32_e32 v86, v2
	v_mov_b32_e32 v87, v2
	v_mov_b32_e32 v88, v2
	v_mov_b32_e32 v89, v2
	v_mov_b32_e32 v94, v2
	v_mov_b32_e32 v95, v2
	v_mov_b32_e32 v96, v2
	v_mov_b32_e32 v97, v2
	v_mov_b32_e32 v102, v2
	v_mov_b32_e32 v103, v2
	v_mov_b32_e32 v104, v2
	v_mov_b32_e32 v105, v2
	v_mov_b32_e32 v110, v2
	v_mov_b32_e32 v111, v2
	v_mov_b32_e32 v112, v2
	v_mov_b32_e32 v113, v2
	v_mov_b32_e32 v118, v2
	v_mov_b32_e32 v119, v2
	v_mov_b32_e32 v120, v2
	v_mov_b32_e32 v121, v2
	v_mov_b32_e32 v126, v2
	v_mov_b32_e32 v127, v2
	v_mov_b32_e32 v128, v2
	v_mov_b32_e32 v129, v2
.LBB0_104:
	s_add_u32 s22, s62, 0xfffc0080
	s_addc_u32 s23, s63, -1
	s_add_i32 s75, 0, 0x10000
	v_add_u32_e32 v151, s75, v147
	ds_read_b128 v[156:159], v151
	ds_read_b128 v[160:163], v151 offset:1024
	ds_read_b128 v[164:167], v151 offset:2048
	ds_read_b128 v[168:171], v151 offset:3072
	s_cmp_eq_u32 s74, 12
	s_cselect_b32 s67, s43, s23
	s_cselect_b32 s66, s61, s22
	s_cselect_b32 s65, s41, s71
	s_cselect_b32 s64, s69, s70
	s_add_i32 m0, s50, 0xc000
	ds_read_b128 v[172:175], v149
	ds_read_b128 v[176:179], v149 offset:1024
	ds_read_b128 v[180:183], v149 offset:2048
	ds_read_b128 v[184:187], v149 offset:3072
	ds_read_b128 v[188:191], v149 offset:4096
	ds_read_b128 v[192:195], v149 offset:5120
	ds_read_b128 v[202:205], v149 offset:6144
	ds_read_b128 v[206:209], v149 offset:7168
	global_load_lds_dwordx4 v138, s[62:63]
	s_add_i32 m0, s50, 0xe000
	s_nop 0
	global_load_lds_dwordx4 v140, s[62:63]
	s_waitcnt lgkmcnt(8)
	s_barrier
	s_waitcnt lgkmcnt(0)
	s_setprio 1
	s_waitcnt lgkmcnt(0)
	v_mfma_f32_16x16x32_bf16 v[126:129], v[156:159], v[172:175], v[126:129]
	v_mfma_f32_16x16x32_bf16 v[118:121], v[164:167], v[172:175], v[118:121]
	v_mfma_f32_16x16x32_bf16 v[110:113], v[156:159], v[180:183], v[110:113]
	v_mfma_f32_16x16x32_bf16 v[102:105], v[164:167], v[180:183], v[102:105]
	v_mfma_f32_16x16x32_bf16 v[94:97], v[156:159], v[188:191], v[94:97]
	v_mfma_f32_16x16x32_bf16 v[86:89], v[164:167], v[188:191], v[86:89]
	v_mfma_f32_16x16x32_bf16 v[78:81], v[156:159], v[202:205], v[78:81]
	v_mfma_f32_16x16x32_bf16 v[70:73], v[164:167], v[202:205], v[70:73]
	v_mfma_f32_16x16x32_bf16 v[126:129], v[160:163], v[176:179], v[126:129]
	v_mfma_f32_16x16x32_bf16 v[118:121], v[168:171], v[176:179], v[118:121]
	v_mfma_f32_16x16x32_bf16 v[110:113], v[160:163], v[184:187], v[110:113]
	v_mfma_f32_16x16x32_bf16 v[102:105], v[168:171], v[184:187], v[102:105]
	v_mfma_f32_16x16x32_bf16 v[94:97], v[160:163], v[192:195], v[94:97]
	v_mfma_f32_16x16x32_bf16 v[86:89], v[168:171], v[192:195], v[86:89]
	v_mfma_f32_16x16x32_bf16 v[78:81], v[160:163], v[206:209], v[78:81]
	v_mfma_f32_16x16x32_bf16 v[70:73], v[168:171], v[206:209], v[70:73]
	s_setprio 0
	s_barrier
; #define PG8_STAGE(bufoff, gbase, voff) do { _Pragma("unroll") for (int _i = 0; _i < 2; ++_i) \
;         __builtin_amdgcn_global_load_lds((const unsigned*)((const char*)(gbase) + (voff)[_i]), (LAS unsigned*)(lds + (bufoff) + ldsw + _i * 8192), 16, 0, 0); } while (0)
; #define PG8_LDA(dst, b, h) do { _Pragma("unroll") for (int m = 0; m < 4; ++m) _Pragma("unroll") for (int k = 0; k < 2; ++k) dst[m][k] = *(const LAS bf16x8*)(lds + PG8_SA(b, h) + aoff + m * 2048 + k * 1024); } while (0)
; #define PG8_LDB(dst, b, h) do { _Pragma("unroll") for (int n = 0; n < 2; ++n) _Pragma("unroll") for (int k = 0; k < 2; ++k) dst[n][k] = *(const LAS bf16x8*)(lds + PG8_SB(b, h) + boff + n * 2048 + k * 1024); } while (0)
; #define PG8_MMA(ai, bj, At, Bt) do { __builtin_amdgcn_s_setprio(1); _Pragma("unroll") for (int m = 0; m < 4; ++m) _Pragma("unroll") for (int n = 0; n < 2; ++n) _Pragma("unroll") for (int k = 0; k < 2; ++k) \
;         acc[ai][bj][m][n] = __builtin_amdgcn_mfma_f32_16x16x32_bf16(Bt[n][k], At[m][k], acc[ai][bj][m][n], 0, 0, 0); __builtin_amdgcn_s_setprio(0); } while (0)
; #define PG8_WAIT_V(n) asm volatile("s_waitcnt vmcnt(" #n ")" ::: "memory")
; #define PG8_WAIT_L(n) asm volatile("s_waitcnt lgkmcnt(" #n ")" ::: "memory")
; #define PG8_BAR __builtin_amdgcn_s_barrier()
; #define PG8_SCHED __builtin_amdgcn_sched_barrier(0)
; template <class Epi>
; __device__ __forceinline__ void gemm_phase(LAS unsigned char* lds, const Gemm g, const StaticOrder& S, const Epi& E) {
;     ...
;             PG8_LDB(B1, 0, 1); PG8_STAGE(PG8_SB(0, 0), b2, voffB);
;             PG8_BAR; PG8_WAIT_L(0); PG8_MMA(0, 1, At, B1); PG8_BAR;
;             PG8_LDA(At, 0, 1); PG8_STAGE(PG8_SA(0, 0), a2, voffA);
;             PG8_BAR; PG8_WAIT_L(0); PG8_MMA(1, 0, At, B0); PG8_BAR; PG8_SCHED;
;             PG8_STAGE(PG8_SB(0, 1), b2 + hB, voffB);
;             PG8_WAIT_V(6); PG8_BAR; PG8_MMA(1, 1, At, B1); PG8_BAR;
;             PG8_LDB(B0, 1, 0); PG8_SCHED; PG8_LDA(At, 1, 0); PG8_STAGE(PG8_SA(0, 1), a2 + hA, voffA);
;             PG8_WAIT_L(8); PG8_BAR; PG8_WAIT_L(0); PG8_MMA(0, 0, At, B0); PG8_BAR; PG8_SCHED;
;             PG8_LDB(B1, 1, 1); PG8_STAGE(PG8_SB(1, 0), b3, voffB);
;             PG8_BAR; PG8_WAIT_L(0); PG8_MMA(0, 1, At, B1); PG8_BAR;
;             PG8_LDA(At, 1, 1); PG8_STAGE(PG8_SA(1, 0), a3, voffA);
	s_add_i32 s76, 0, 0x14000
	s_add_i32 s22, s75, s48
	v_add_u32_e32 v151, s76, v147
	s_mov_b32 m0, s22
	ds_read_b128 v[210:213], v151
	ds_read_b128 v[214:217], v151 offset:1024
	ds_read_b128 v[218:221], v151 offset:2048
	ds_read_b128 v[222:225], v151 offset:3072
	global_load_lds_dwordx4 v0, s[64:65]
	s_add_i32 m0, s22, 0x2000
	s_nop 0
	global_load_lds_dwordx4 v134, s[64:65]
	s_barrier
	s_waitcnt lgkmcnt(0)
	s_setprio 1
	s_waitcnt lgkmcnt(0)
	v_mfma_f32_16x16x32_bf16 v[122:125], v[210:213], v[172:175], v[122:125]
	v_mfma_f32_16x16x32_bf16 v[114:117], v[218:221], v[172:175], v[114:117]
	v_mfma_f32_16x16x32_bf16 v[106:109], v[210:213], v[180:183], v[106:109]
	v_mfma_f32_16x16x32_bf16 v[98:101], v[218:221], v[180:183], v[98:101]
	v_mfma_f32_16x16x32_bf16 v[90:93], v[210:213], v[188:191], v[90:93]
	v_mfma_f32_16x16x32_bf16 v[82:85], v[218:221], v[188:191], v[82:85]
	v_mfma_f32_16x16x32_bf16 v[74:77], v[210:213], v[202:205], v[74:77]
	v_mfma_f32_16x16x32_bf16 v[66:69], v[218:221], v[202:205], v[66:69]
	v_mfma_f32_16x16x32_bf16 v[122:125], v[214:217], v[176:179], v[122:125]
	v_mfma_f32_16x16x32_bf16 v[114:117], v[222:225], v[176:179], v[114:117]
	v_mfma_f32_16x16x32_bf16 v[106:109], v[214:217], v[184:187], v[106:109]
	v_mfma_f32_16x16x32_bf16 v[98:101], v[222:225], v[184:187], v[98:101]
	v_mfma_f32_16x16x32_bf16 v[90:93], v[214:217], v[192:195], v[90:93]
	v_mfma_f32_16x16x32_bf16 v[82:85], v[222:225], v[192:195], v[82:85]
	v_mfma_f32_16x16x32_bf16 v[74:77], v[214:217], v[206:209], v[74:77]
	v_mfma_f32_16x16x32_bf16 v[66:69], v[222:225], v[206:209], v[66:69]
	s_setprio 0
	s_mov_b32 m0, s50
	s_barrier
	ds_read_b128 v[172:175], v149 offset:16384
	ds_read_b128 v[176:179], v149 offset:17408
	ds_read_b128 v[180:183], v149 offset:18432
	ds_read_b128 v[184:187], v149 offset:19456
	ds_read_b128 v[188:191], v149 offset:20480
	ds_read_b128 v[192:195], v149 offset:21504
	ds_read_b128 v[202:205], v149 offset:22528
	ds_read_b128 v[206:209], v149 offset:23552
	global_load_lds_dwordx4 v130, s[66:67]
	s_mov_b32 m0, s51
	s_nop 0
	global_load_lds_dwordx4 v132, s[66:67]
	s_barrier
	s_waitcnt lgkmcnt(0)
	s_setprio 1
	s_waitcnt lgkmcnt(0)
	v_mfma_f32_16x16x32_bf16 v[62:65], v[156:159], v[172:175], v[62:65]
	v_mfma_f32_16x16x32_bf16 v[54:57], v[164:167], v[172:175], v[54:57]
	v_mfma_f32_16x16x32_bf16 v[46:49], v[156:159], v[180:183], v[46:49]
	v_mfma_f32_16x16x32_bf16 v[38:41], v[164:167], v[180:183], v[38:41]
	v_mfma_f32_16x16x32_bf16 v[30:33], v[156:159], v[188:191], v[30:33]
	v_mfma_f32_16x16x32_bf16 v[22:25], v[164:167], v[188:191], v[22:25]
	v_mfma_f32_16x16x32_bf16 v[14:17], v[156:159], v[202:205], v[14:17]
	v_mfma_f32_16x16x32_bf16 v[6:9], v[164:167], v[202:205], v[6:9]
	v_mfma_f32_16x16x32_bf16 v[62:65], v[160:163], v[176:179], v[62:65]
	v_mfma_f32_16x16x32_bf16 v[54:57], v[168:171], v[176:179], v[54:57]
	v_mfma_f32_16x16x32_bf16 v[46:49], v[160:163], v[184:187], v[46:49]
	v_mfma_f32_16x16x32_bf16 v[38:41], v[168:171], v[184:187], v[38:41]
	v_mfma_f32_16x16x32_bf16 v[30:33], v[160:163], v[192:195], v[30:33]
	v_mfma_f32_16x16x32_bf16 v[22:25], v[168:171], v[192:195], v[22:25]
	v_mfma_f32_16x16x32_bf16 v[14:17], v[160:163], v[206:209], v[14:17]
	v_mfma_f32_16x16x32_bf16 v[6:9], v[168:171], v[206:209], v[6:9]
	s_setprio 0
	s_barrier
	s_add_u32 s22, s64, 0x40000
	s_addc_u32 s23, s65, 0
	s_add_i32 s75, s76, s48
	s_mov_b32 m0, s75
	s_nop 0
	global_load_lds_dwordx4 v0, s[22:23]
	s_add_i32 m0, s75, 0x2000
	s_nop 0
	global_load_lds_dwordx4 v134, s[22:23]
	s_waitcnt vmcnt(6)
	s_barrier
	s_setprio 1
	v_mfma_f32_16x16x32_bf16 v[58:61], v[210:213], v[172:175], v[58:61]
	v_mfma_f32_16x16x32_bf16 v[50:53], v[218:221], v[172:175], v[50:53]
	v_mfma_f32_16x16x32_bf16 v[42:45], v[210:213], v[180:183], v[42:45]
	v_mfma_f32_16x16x32_bf16 v[34:37], v[218:221], v[180:183], v[34:37]
	v_mfma_f32_16x16x32_bf16 v[26:29], v[210:213], v[188:191], v[26:29]
	v_mfma_f32_16x16x32_bf16 v[18:21], v[218:221], v[188:191], v[18:21]
	v_mfma_f32_16x16x32_bf16 v[10:13], v[210:213], v[202:205], v[10:13]
	v_mfma_f32_16x16x32_bf16 v[2:5], v[218:221], v[202:205], v[2:5]
	v_mfma_f32_16x16x32_bf16 v[58:61], v[214:217], v[176:179], v[58:61]
	v_mfma_f32_16x16x32_bf16 v[50:53], v[222:225], v[176:179], v[50:53]
	v_mfma_f32_16x16x32_bf16 v[42:45], v[214:217], v[184:187], v[42:45]
	v_mfma_f32_16x16x32_bf16 v[34:37], v[222:225], v[184:187], v[34:37]
	v_mfma_f32_16x16x32_bf16 v[26:29], v[214:217], v[192:195], v[26:29]
	v_mfma_f32_16x16x32_bf16 v[18:21], v[222:225], v[192:195], v[18:21]
	v_mfma_f32_16x16x32_bf16 v[10:13], v[214:217], v[206:209], v[10:13]
	v_mfma_f32_16x16x32_bf16 v[2:5], v[222:225], v[206:209], v[2:5]
	s_setprio 0
	s_add_i32 s75, 0, 0x18000
	v_add_u32_e32 v151, s75, v147
	s_barrier
	ds_read_b128 v[156:159], v151
	ds_read_b128 v[160:163], v151 offset:1024
	ds_read_b128 v[164:167], v151 offset:2048
	ds_read_b128 v[168:171], v151 offset:3072
	s_add_u32 s22, s66, 0x40000
	s_addc_u32 s23, s67, 0
	s_mov_b32 m0, s53
	ds_read_b128 v[172:175], v149 offset:32768
	ds_read_b128 v[176:179], v149 offset:33792
	ds_read_b128 v[180:183], v149 offset:34816
	ds_read_b128 v[184:187], v149 offset:35840
	ds_read_b128 v[188:191], v149 offset:36864
	ds_read_b128 v[192:195], v149 offset:37888
	ds_read_b128 v[202:205], v149 offset:38912
	ds_read_b128 v[206:209], v149 offset:39936
	global_load_lds_dwordx4 v130, s[22:23]
	s_mov_b32 m0, s54
	s_nop 0
	global_load_lds_dwordx4 v132, s[22:23]
	s_waitcnt lgkmcnt(8)
	s_barrier
; #define PG8_STAGE(bufoff, gbase, voff) do { _Pragma("unroll") for (int _i = 0; _i < 2; ++_i) \
;         __builtin_amdgcn_global_load_lds((const unsigned*)((const char*)(gbase) + (voff)[_i]), (LAS unsigned*)(lds + (bufoff) + ldsw + _i * 8192), 16, 0, 0); } while (0)
; #define PG8_LDA(dst, b, h) do { _Pragma("unroll") for (int m = 0; m < 4; ++m) _Pragma("unroll") for (int k = 0; k < 2; ++k) dst[m][k] = *(const LAS bf16x8*)(lds + PG8_SA(b, h) + aoff + m * 2048 + k * 1024); } while (0)
; #define PG8_LDB(dst, b, h) do { _Pragma("unroll") for (int n = 0; n < 2; ++n) _Pragma("unroll") for (int k = 0; k < 2; ++k) dst[n][k] = *(const LAS bf16x8*)(lds + PG8_SB(b, h) + boff + n * 2048 + k * 1024); } while (0)
; #define PG8_MMA(ai, bj, At, Bt) do { __builtin_amdgcn_s_setprio(1); _Pragma("unroll") for (int m = 0; m < 4; ++m) _Pragma("unroll") for (int n = 0; n < 2; ++n) _Pragma("unroll") for (int k = 0; k < 2; ++k) \
;         acc[ai][bj][m][n] = __builtin_amdgcn_mfma_f32_16x16x32_bf16(Bt[n][k], At[m][k], acc[ai][bj][m][n], 0, 0, 0); __builtin_amdgcn_s_setprio(0); } while (0)
; #define PG8_WAIT_V(n) asm volatile("s_waitcnt vmcnt(" #n ")" ::: "memory")
; #define PG8_WAIT_L(n) asm volatile("s_waitcnt lgkmcnt(" #n ")" ::: "memory")
; #define PG8_BAR __builtin_amdgcn_s_barrier()
; #define PG8_SCHED __builtin_amdgcn_sched_barrier(0)
; template <class Epi>
; __device__ __forceinline__ void gemm_phase(LAS unsigned char* lds, const Gemm g, const StaticOrder& S, const Epi& E) {
;     ...
;             PG8_WAIT_L(8); PG8_BAR; PG8_WAIT_L(0); PG8_MMA(0, 0, At, B0); PG8_BAR; PG8_SCHED;
;             PG8_LDB(B1, 1, 1); PG8_STAGE(PG8_SB(1, 0), b3, voffB);
;             PG8_BAR; PG8_WAIT_L(0); PG8_MMA(0, 1, At, B1); PG8_BAR;
;             PG8_LDA(At, 1, 1); PG8_STAGE(PG8_SA(1, 0), a3, voffA);
;             PG8_BAR; PG8_WAIT_L(0); PG8_MMA(1, 0, At, B0); PG8_BAR; PG8_SCHED;
;             PG8_STAGE(PG8_SB(1, 1), b3 + hB, voffB);
;             PG8_WAIT_V(6); PG8_BAR; PG8_MMA(1, 1, At, B1); PG8_BAR;
	s_waitcnt lgkmcnt(0)
	s_setprio 1
	s_waitcnt lgkmcnt(0)
	v_mfma_f32_16x16x32_bf16 v[126:129], v[156:159], v[172:175], v[126:129]
	v_mfma_f32_16x16x32_bf16 v[118:121], v[164:167], v[172:175], v[118:121]
	v_mfma_f32_16x16x32_bf16 v[110:113], v[156:159], v[180:183], v[110:113]
	v_mfma_f32_16x16x32_bf16 v[102:105], v[164:167], v[180:183], v[102:105]
	v_mfma_f32_16x16x32_bf16 v[94:97], v[156:159], v[188:191], v[94:97]
	v_mfma_f32_16x16x32_bf16 v[86:89], v[164:167], v[188:191], v[86:89]
	v_mfma_f32_16x16x32_bf16 v[78:81], v[156:159], v[202:205], v[78:81]
	v_mfma_f32_16x16x32_bf16 v[70:73], v[164:167], v[202:205], v[70:73]
	v_mfma_f32_16x16x32_bf16 v[126:129], v[160:163], v[176:179], v[126:129]
	v_mfma_f32_16x16x32_bf16 v[118:121], v[168:171], v[176:179], v[118:121]
	v_mfma_f32_16x16x32_bf16 v[110:113], v[160:163], v[184:187], v[110:113]
	v_mfma_f32_16x16x32_bf16 v[102:105], v[168:171], v[184:187], v[102:105]
	v_mfma_f32_16x16x32_bf16 v[94:97], v[160:163], v[192:195], v[94:97]
	v_mfma_f32_16x16x32_bf16 v[86:89], v[168:171], v[192:195], v[86:89]
	v_mfma_f32_16x16x32_bf16 v[78:81], v[160:163], v[206:209], v[78:81]
	v_mfma_f32_16x16x32_bf16 v[70:73], v[168:171], v[206:209], v[70:73]
	s_setprio 0
	s_barrier
	s_add_i32 s22, s75, s48
	v_add_u32_e32 v151, 0x1c000, v147
	s_add_u32 s100, s64, 0x80
	s_addc_u32 s101, s65, 0
	s_mov_b32 m0, s22
	ds_read_b128 v[210:213], v151
	ds_read_b128 v[214:217], v151 offset:1024
	ds_read_b128 v[218:221], v151 offset:2048
	ds_read_b128 v[222:225], v151 offset:3072
	global_load_lds_dwordx4 v0, s[100:101]
	s_add_i32 m0, s22, 0x2000
	s_nop 0
	global_load_lds_dwordx4 v134, s[100:101]
	s_barrier
	s_waitcnt lgkmcnt(0)
	s_setprio 1
	s_waitcnt lgkmcnt(0)
	v_mfma_f32_16x16x32_bf16 v[122:125], v[210:213], v[172:175], v[122:125]
	v_mfma_f32_16x16x32_bf16 v[114:117], v[218:221], v[172:175], v[114:117]
	v_mfma_f32_16x16x32_bf16 v[106:109], v[210:213], v[180:183], v[106:109]
	v_mfma_f32_16x16x32_bf16 v[98:101], v[218:221], v[180:183], v[98:101]
	v_mfma_f32_16x16x32_bf16 v[90:93], v[210:213], v[188:191], v[90:93]
	v_mfma_f32_16x16x32_bf16 v[82:85], v[218:221], v[188:191], v[82:85]
	v_mfma_f32_16x16x32_bf16 v[74:77], v[210:213], v[202:205], v[74:77]
	v_mfma_f32_16x16x32_bf16 v[66:69], v[218:221], v[202:205], v[66:69]
	v_mfma_f32_16x16x32_bf16 v[122:125], v[214:217], v[176:179], v[122:125]
	v_mfma_f32_16x16x32_bf16 v[114:117], v[222:225], v[176:179], v[114:117]
	v_mfma_f32_16x16x32_bf16 v[106:109], v[214:217], v[184:187], v[106:109]
	v_mfma_f32_16x16x32_bf16 v[98:101], v[222:225], v[184:187], v[98:101]
	v_mfma_f32_16x16x32_bf16 v[90:93], v[214:217], v[192:195], v[90:93]
	v_mfma_f32_16x16x32_bf16 v[82:85], v[222:225], v[192:195], v[82:85]
	v_mfma_f32_16x16x32_bf16 v[74:77], v[214:217], v[206:209], v[74:77]
	v_mfma_f32_16x16x32_bf16 v[66:69], v[222:225], v[206:209], v[66:69]
	s_setprio 0
	s_mov_b32 m0, s56
	s_add_u32 s100, s66, 0x80
	s_addc_u32 s101, s67, 0
	s_barrier
	ds_read_b128 v[172:175], v149 offset:49152
	ds_read_b128 v[176:179], v149 offset:50176
	ds_read_b128 v[180:183], v149 offset:51200
	ds_read_b128 v[184:187], v149 offset:52224
	ds_read_b128 v[188:191], v149 offset:53248
	ds_read_b128 v[192:195], v149 offset:54272
	ds_read_b128 v[202:205], v149 offset:55296
	ds_read_b128 v[206:209], v149 offset:56320
	global_load_lds_dwordx4 v130, s[100:101]
	s_mov_b32 m0, s57
	s_nop 0
	global_load_lds_dwordx4 v132, s[100:101]
	s_barrier
	s_waitcnt lgkmcnt(0)
	s_setprio 1
	s_waitcnt lgkmcnt(0)
	v_mfma_f32_16x16x32_bf16 v[62:65], v[156:159], v[172:175], v[62:65]
	v_mfma_f32_16x16x32_bf16 v[54:57], v[164:167], v[172:175], v[54:57]
	v_mfma_f32_16x16x32_bf16 v[46:49], v[156:159], v[180:183], v[46:49]
	v_mfma_f32_16x16x32_bf16 v[38:41], v[164:167], v[180:183], v[38:41]
	v_mfma_f32_16x16x32_bf16 v[30:33], v[156:159], v[188:191], v[30:33]
	v_mfma_f32_16x16x32_bf16 v[22:25], v[164:167], v[188:191], v[22:25]
	v_mfma_f32_16x16x32_bf16 v[14:17], v[156:159], v[202:205], v[14:17]
	v_mfma_f32_16x16x32_bf16 v[6:9], v[164:167], v[202:205], v[6:9]
	v_mfma_f32_16x16x32_bf16 v[62:65], v[160:163], v[176:179], v[62:65]
	v_mfma_f32_16x16x32_bf16 v[54:57], v[168:171], v[176:179], v[54:57]
	v_mfma_f32_16x16x32_bf16 v[46:49], v[160:163], v[184:187], v[46:49]
	v_mfma_f32_16x16x32_bf16 v[38:41], v[168:171], v[184:187], v[38:41]
	v_mfma_f32_16x16x32_bf16 v[30:33], v[160:163], v[192:195], v[30:33]
	v_mfma_f32_16x16x32_bf16 v[22:25], v[168:171], v[192:195], v[22:25]
	v_mfma_f32_16x16x32_bf16 v[14:17], v[160:163], v[206:209], v[14:17]
	v_mfma_f32_16x16x32_bf16 v[6:9], v[168:171], v[206:209], v[6:9]
	s_setprio 0
	s_barrier
	s_add_u32 s22, s64, 0x40080
	s_addc_u32 s23, s65, 0
	s_add_i32 s64, s48, 0x1c000
	s_mov_b32 m0, s64
	s_nop 0
	global_load_lds_dwordx4 v0, s[22:23]
	s_add_i32 m0, s64, 0x2000
	s_nop 0
	global_load_lds_dwordx4 v134, s[22:23]
	s_waitcnt vmcnt(6)
	s_barrier
	s_setprio 1
	v_mfma_f32_16x16x32_bf16 v[58:61], v[210:213], v[172:175], v[58:61]
	v_mfma_f32_16x16x32_bf16 v[50:53], v[218:221], v[172:175], v[50:53]
	v_mfma_f32_16x16x32_bf16 v[42:45], v[210:213], v[180:183], v[42:45]
	v_mfma_f32_16x16x32_bf16 v[34:37], v[218:221], v[180:183], v[34:37]
	v_mfma_f32_16x16x32_bf16 v[26:29], v[210:213], v[188:191], v[26:29]
	v_mfma_f32_16x16x32_bf16 v[18:21], v[218:221], v[188:191], v[18:21]
	v_mfma_f32_16x16x32_bf16 v[10:13], v[210:213], v[202:205], v[10:13]
	v_mfma_f32_16x16x32_bf16 v[2:5], v[218:221], v[202:205], v[2:5]
	v_mfma_f32_16x16x32_bf16 v[58:61], v[214:217], v[176:179], v[58:61]
	v_mfma_f32_16x16x32_bf16 v[50:53], v[222:225], v[176:179], v[50:53]
	v_mfma_f32_16x16x32_bf16 v[42:45], v[214:217], v[184:187], v[42:45]
	v_mfma_f32_16x16x32_bf16 v[34:37], v[222:225], v[184:187], v[34:37]
	v_mfma_f32_16x16x32_bf16 v[26:29], v[214:217], v[192:195], v[26:29]
	v_mfma_f32_16x16x32_bf16 v[18:21], v[222:225], v[192:195], v[18:21]
	v_mfma_f32_16x16x32_bf16 v[10:13], v[214:217], v[206:209], v[10:13]
	v_mfma_f32_16x16x32_bf16 v[2:5], v[222:225], v[206:209], v[2:5]
	s_setprio 0
	s_add_i32 s74, s74, 2
	s_add_u32 s62, s62, 0x100
	s_addc_u32 s63, s63, 0
	s_add_u32 s70, s70, 0x100
	s_addc_u32 s71, s71, 0
	s_cmp_gt_u32 s74, 13
	s_barrier
; __device__ __forceinline__ float siluf_(float x) { return x * sigmoidf_(x); }
; __device__ __forceinline__ u32x4 pack8(const f32x4 a, const f32x4 b) { u32x4 w; w.x = cvt_pk_bf16(a[0], a[1]); w.y = cvt_pk_bf16(a[2], a[3]); w.z = cvt_pk_bf16(b[0], b[1]); w.w = cvt_pk_bf16(b[2], b[3]); return w; }
;     __device__ __forceinline__ void operator()(const Acc& acc, const Unit& u, int wr, int wc, int fr, int fq, const RsPre& pr) const {
;         asm volatile("" : "+v"(fr), "+v"(fq));
;         const int row0 = u.pm * 256 + wr * 64 + fr, col0 = u.pn * 128 + wc * 32 + 8 * fq;
;         const float (&rs)[2][4] = pr.rs;
; #pragma unroll
;         for (int ai = 0; ai < 2; ++ai)
; #pragma unroll
;             for (int m = 0; m < 4; ++m) { f32x4 o[2];
; #pragma unroll
;                 for (int n = 0; n < 2; ++n) { const f32x4 a1 = acc[ai][0][m][n] * rs[ai][m], a3 = acc[ai][1][m][n] * rs[ai][m];
;                     o[n] = (f32x4){siluf_(a1[0]) * a3[0], siluf_(a1[1]) * a3[1], siluf_(a1[2]) * a3[2], siluf_(a1[3]) * a3[3]}; }
;                 *(u32x4*)(ff + (size_t)(row0 + ai * 128 + m * 16) * DFF + col0) = pack8(o[0], o[1]); }
	s_cbranch_scc0 .LBB0_104
	v_mov_b32_e32 v151, v137
	v_mov_b32_e32 v153, v143
	s_lshl_b32 s22, s60, 8
	s_add_i32 s22, s22, s49
	v_add_u32_e32 v151, s22, v151
	s_lshl_b32 s22, s33, 7
	s_or_b32 s22, s22, s55
	s_waitcnt vmcnt(0)
	v_pk_mul_f32 v[126:127], v[154:155], v[126:127] op_sel_hi:[0,1]
	v_lshl_add_u32 v156, v153, 3, s22
	v_mul_f32_e32 v153, 0xbfb8aa3b, v126
	v_exp_f32_e32 v153, v153
	v_pk_mul_f32 v[128:129], v[154:155], v[128:129] op_sel_hi:[0,1]
	v_pk_mul_f32 v[122:123], v[154:155], v[122:123] op_sel_hi:[0,1]
	v_pk_mul_f32 v[124:125], v[154:155], v[124:125] op_sel_hi:[0,1]
	v_add_f32_e32 v153, 1.0, v153
	v_rcp_f32_e32 v158, v153
	v_mul_f32_e32 v153, 0xbfb8aa3b, v127
	v_exp_f32_e32 v153, v153
	v_pk_mul_f32 v[118:119], v[154:155], v[118:119] op_sel_hi:[0,1]
	v_pk_mul_f32 v[120:121], v[154:155], v[120:121] op_sel_hi:[0,1]
	v_pk_mul_f32 v[114:115], v[154:155], v[114:115] op_sel_hi:[0,1]
	v_add_f32_e32 v153, 1.0, v153
	v_rcp_f32_e32 v159, v153
	v_pk_mul_f32 v[116:117], v[154:155], v[116:117] op_sel_hi:[0,1]
	s_movk_i32 s0, 0x1600
	v_pk_mul_f32 v[126:127], v[126:127], v[158:159]
	v_pk_mul_f32 v[110:111], v[152:153], v[110:111] op_sel_hi:[0,1]
	v_pk_mul_f32 v[122:123], v[126:127], v[122:123]
	v_mul_f32_e32 v126, 0xbfb8aa3b, v128
	v_mul_f32_e32 v127, 0xbfb8aa3b, v129
	v_exp_f32_e32 v126, v126
	v_exp_f32_e32 v127, v127
	v_pk_mul_f32 v[112:113], v[152:153], v[112:113] op_sel_hi:[0,1]
	v_pk_mul_f32 v[106:107], v[152:153], v[106:107] op_sel_hi:[0,1]
	v_add_f32_e32 v126, 1.0, v126
	v_add_f32_e32 v127, 1.0, v127
	v_rcp_f32_e32 v126, v126
	v_rcp_f32_e32 v127, v127
	v_pk_mul_f32 v[108:109], v[152:153], v[108:109] op_sel_hi:[0,1]
	v_pk_mul_f32 v[102:103], v[152:153], v[102:103] op_sel_hi:[0,1]
	v_pk_mul_f32 v[104:105], v[152:153], v[104:105] op_sel_hi:[0,1]
	v_pk_mul_f32 v[126:127], v[128:129], v[126:127]
	v_pk_mul_f32 v[98:99], v[152:153], v[98:99] op_sel_hi:[0,1]
	v_pk_mul_f32 v[124:125], v[126:127], v[124:125]
	v_mul_f32_e32 v126, 0xbfb8aa3b, v118
	v_mul_f32_e32 v127, 0xbfb8aa3b, v119
	v_exp_f32_e32 v126, v126
	v_exp_f32_e32 v127, v127
	v_pk_mul_f32 v[100:101], v[152:153], v[100:101] op_sel_hi:[0,1]
	v_pk_mul_f32 v[94:95], v[150:151], v[94:95] op_sel_hi:[0,1]
	v_add_f32_e32 v126, 1.0, v126
	v_add_f32_e32 v127, 1.0, v127
	v_rcp_f32_e32 v126, v126
	v_rcp_f32_e32 v127, v127
	v_pk_mul_f32 v[96:97], v[150:151], v[96:97] op_sel_hi:[0,1]
	v_pk_mul_f32 v[90:91], v[150:151], v[90:91] op_sel_hi:[0,1]
	v_pk_mul_f32 v[92:93], v[150:151], v[92:93] op_sel_hi:[0,1]
	v_pk_mul_f32 v[118:119], v[118:119], v[126:127]
	v_pk_mul_f32 v[86:87], v[150:151], v[86:87] op_sel_hi:[0,1]
	v_pk_mul_f32 v[114:115], v[118:119], v[114:115]
	v_mul_f32_e32 v118, 0xbfb8aa3b, v120
	v_mul_f32_e32 v119, 0xbfb8aa3b, v121
	v_exp_f32_e32 v118, v118
	v_exp_f32_e32 v119, v119
	v_pk_mul_f32 v[88:89], v[150:151], v[88:89] op_sel_hi:[0,1]
	v_pk_mul_f32 v[82:83], v[150:151], v[82:83] op_sel_hi:[0,1]
	v_add_f32_e32 v118, 1.0, v118
	v_add_f32_e32 v119, 1.0, v119
	v_rcp_f32_e32 v118, v118
	v_rcp_f32_e32 v119, v119
	v_pk_mul_f32 v[84:85], v[150:151], v[84:85] op_sel_hi:[0,1]
	v_pk_mul_f32 v[78:79], v[148:149], v[78:79] op_sel_hi:[0,1]
	v_pk_mul_f32 v[80:81], v[148:149], v[80:81] op_sel_hi:[0,1]
	v_pk_mul_f32 v[118:119], v[120:121], v[118:119]
	v_cvt_pk_bf16_f32 v120, v114, v115
	v_pk_mul_f32 v[116:117], v[118:119], v[116:117]
	v_cvt_pk_bf16_f32 v118, v122, v123
	v_cvt_pk_bf16_f32 v121, v116, v117
	v_lshlrev_b32_e32 v116, 1, v156
	v_mad_u32_u24 v114, v151, s0, v116
	v_cvt_pk_bf16_f32 v119, v124, v125
	global_store_dwordx4 v114, v[118:121], s[20:21]
	v_pk_mul_f32 v[74:75], v[148:149], v[74:75] op_sel_hi:[0,1]
	v_pk_mul_f32 v[76:77], v[148:149], v[76:77] op_sel_hi:[0,1]
	v_mul_f32_e32 v118, 0xbfb8aa3b, v110
	v_mul_f32_e32 v119, 0xbfb8aa3b, v111
	v_exp_f32_e32 v118, v118
	v_exp_f32_e32 v119, v119
	v_pk_mul_f32 v[70:71], v[148:149], v[70:71] op_sel_hi:[0,1]
	v_pk_mul_f32 v[72:73], v[148:149], v[72:73] op_sel_hi:[0,1]
	v_add_f32_e32 v118, 1.0, v118
	v_add_f32_e32 v119, 1.0, v119
	v_rcp_f32_e32 v118, v118
	v_rcp_f32_e32 v119, v119
	v_pk_mul_f32 v[66:67], v[148:149], v[66:67] op_sel_hi:[0,1]
	v_pk_mul_f32 v[68:69], v[148:149], v[68:69] op_sel_hi:[0,1]
	v_pk_mul_f32 v[62:63], v[146:147], v[62:63] op_sel_hi:[0,1]
	v_pk_mul_f32 v[110:111], v[110:111], v[118:119]
	v_pk_mul_f32 v[64:65], v[146:147], v[64:65] op_sel_hi:[0,1]
	v_pk_mul_f32 v[106:107], v[110:111], v[106:107]
	v_mul_f32_e32 v110, 0xbfb8aa3b, v112
	v_mul_f32_e32 v111, 0xbfb8aa3b, v113
	v_exp_f32_e32 v110, v110
	v_exp_f32_e32 v111, v111
	v_pk_mul_f32 v[58:59], v[146:147], v[58:59] op_sel_hi:[0,1]
	v_pk_mul_f32 v[60:61], v[146:147], v[60:61] op_sel_hi:[0,1]
	v_add_f32_e32 v110, 1.0, v110
	v_add_f32_e32 v111, 1.0, v111
	v_rcp_f32_e32 v110, v110
	v_rcp_f32_e32 v111, v111
	v_pk_mul_f32 v[54:55], v[146:147], v[54:55] op_sel_hi:[0,1]
	v_pk_mul_f32 v[56:57], v[146:147], v[56:57] op_sel_hi:[0,1]
	v_pk_mul_f32 v[50:51], v[146:147], v[50:51] op_sel_hi:[0,1]
	v_pk_mul_f32 v[110:111], v[112:113], v[110:111]
	v_pk_mul_f32 v[52:53], v[146:147], v[52:53] op_sel_hi:[0,1]
	v_pk_mul_f32 v[108:109], v[110:111], v[108:109]
	v_mul_f32_e32 v110, 0xbfb8aa3b, v102
	v_mul_f32_e32 v111, 0xbfb8aa3b, v103
	v_exp_f32_e32 v110, v110
	v_exp_f32_e32 v111, v111
	v_pk_mul_f32 v[46:47], v[144:145], v[46:47] op_sel_hi:[0,1]
	v_pk_mul_f32 v[48:49], v[144:145], v[48:49] op_sel_hi:[0,1]
	v_add_f32_e32 v110, 1.0, v110
	v_add_f32_e32 v111, 1.0, v111
	v_rcp_f32_e32 v110, v110
	v_rcp_f32_e32 v111, v111
	v_pk_mul_f32 v[42:43], v[144:145], v[42:43] op_sel_hi:[0,1]
	v_pk_mul_f32 v[44:45], v[144:145], v[44:45] op_sel_hi:[0,1]
	v_pk_mul_f32 v[38:39], v[144:145], v[38:39] op_sel_hi:[0,1]
; __device__ __forceinline__ float siluf_(float x) { return x * sigmoidf_(x); }
; __device__ __forceinline__ u32x4 pack8(const f32x4 a, const f32x4 b) { u32x4 w; w.x = cvt_pk_bf16(a[0], a[1]); w.y = cvt_pk_bf16(a[2], a[3]); w.z = cvt_pk_bf16(b[0], b[1]); w.w = cvt_pk_bf16(b[2], b[3]); return w; }
;     __device__ __forceinline__ void operator()(const Acc& acc, const Unit& u, int wr, int wc, int fr, int fq, const RsPre& pr) const {
;         asm volatile("" : "+v"(fr), "+v"(fq));
;         const int row0 = u.pm * 256 + wr * 64 + fr, col0 = u.pn * 128 + wc * 32 + 8 * fq;
;         const float (&rs)[2][4] = pr.rs;
; #pragma unroll
;         for (int ai = 0; ai < 2; ++ai)
; #pragma unroll
;             for (int m = 0; m < 4; ++m) { f32x4 o[2];
; #pragma unroll
;                 for (int n = 0; n < 2; ++n) { const f32x4 a1 = acc[ai][0][m][n] * rs[ai][m], a3 = acc[ai][1][m][n] * rs[ai][m];
;                     o[n] = (f32x4){siluf_(a1[0]) * a3[0], siluf_(a1[1]) * a3[1], siluf_(a1[2]) * a3[2], siluf_(a1[3]) * a3[3]}; }
;                 *(u32x4*)(ff + (size_t)(row0 + ai * 128 + m * 16) * DFF + col0) = pack8(o[0], o[1]); }
	v_pk_mul_f32 v[102:103], v[102:103], v[110:111]
	v_pk_mul_f32 v[40:41], v[144:145], v[40:41] op_sel_hi:[0,1]
	v_pk_mul_f32 v[102:103], v[102:103], v[98:99]
	v_mul_f32_e32 v98, 0xbfb8aa3b, v104
	v_mul_f32_e32 v99, 0xbfb8aa3b, v105
	v_exp_f32_e32 v98, v98
	v_exp_f32_e32 v99, v99
	v_pk_mul_f32 v[34:35], v[144:145], v[34:35] op_sel_hi:[0,1]
	v_pk_mul_f32 v[36:37], v[144:145], v[36:37] op_sel_hi:[0,1]
	v_add_f32_e32 v98, 1.0, v98
	v_add_f32_e32 v99, 1.0, v99
	v_rcp_f32_e32 v98, v98
	v_rcp_f32_e32 v99, v99
	v_pk_mul_f32 v[30:31], v[142:143], v[30:31] op_sel_hi:[0,1]
	v_pk_mul_f32 v[32:33], v[142:143], v[32:33] op_sel_hi:[0,1]
	v_pk_mul_f32 v[26:27], v[142:143], v[26:27] op_sel_hi:[0,1]
	v_pk_mul_f32 v[98:99], v[104:105], v[98:99]
	v_pk_mul_f32 v[28:29], v[142:143], v[28:29] op_sel_hi:[0,1]
	v_pk_mul_f32 v[104:105], v[98:99], v[100:101]
	v_cvt_pk_bf16_f32 v100, v102, v103
	v_cvt_pk_bf16_f32 v98, v106, v107
	v_cvt_pk_bf16_f32 v99, v108, v109
	v_cvt_pk_bf16_f32 v101, v104, v105
	v_add_u32_e32 v102, 0x16000, v114
	global_store_dwordx4 v102, v[98:101], s[20:21]
	v_pk_mul_f32 v[22:23], v[142:143], v[22:23] op_sel_hi:[0,1]
	v_pk_mul_f32 v[24:25], v[142:143], v[24:25] op_sel_hi:[0,1]
	v_mul_f32_e32 v98, 0xbfb8aa3b, v94
	v_mul_f32_e32 v99, 0xbfb8aa3b, v95
	v_exp_f32_e32 v98, v98
	v_exp_f32_e32 v99, v99
	v_pk_mul_f32 v[18:19], v[142:143], v[18:19] op_sel_hi:[0,1]
	v_pk_mul_f32 v[20:21], v[142:143], v[20:21] op_sel_hi:[0,1]
	v_add_f32_e32 v98, 1.0, v98
	v_add_f32_e32 v99, 1.0, v99
	v_rcp_f32_e32 v98, v98
	v_rcp_f32_e32 v99, v99
	v_pk_mul_f32 v[14:15], v[136:137], v[14:15] op_sel_hi:[0,1]
	v_pk_mul_f32 v[16:17], v[136:137], v[16:17] op_sel_hi:[0,1]
	v_pk_mul_f32 v[10:11], v[136:137], v[10:11] op_sel_hi:[0,1]
	v_pk_mul_f32 v[94:95], v[94:95], v[98:99]
	v_pk_mul_f32 v[12:13], v[136:137], v[12:13] op_sel_hi:[0,1]
	v_pk_mul_f32 v[90:91], v[94:95], v[90:91]
	v_mul_f32_e32 v94, 0xbfb8aa3b, v96
	v_mul_f32_e32 v95, 0xbfb8aa3b, v97
	v_exp_f32_e32 v94, v94
	v_exp_f32_e32 v95, v95
	v_pk_mul_f32 v[6:7], v[136:137], v[6:7] op_sel_hi:[0,1]
	v_pk_mul_f32 v[8:9], v[136:137], v[8:9] op_sel_hi:[0,1]
	v_add_f32_e32 v94, 1.0, v94
	v_add_f32_e32 v95, 1.0, v95
	v_rcp_f32_e32 v94, v94
	v_rcp_f32_e32 v95, v95
	v_pk_mul_f32 v[2:3], v[136:137], v[2:3] op_sel_hi:[0,1]
	v_pk_mul_f32 v[4:5], v[136:137], v[4:5] op_sel_hi:[0,1]
	s_mov_b64 s[60:61], -1
	v_pk_mul_f32 v[94:95], v[96:97], v[94:95]
	s_and_b64 vcc, vcc, exec
	v_pk_mul_f32 v[92:93], v[94:95], v[92:93]
	v_mul_f32_e32 v94, 0xbfb8aa3b, v86
	v_mul_f32_e32 v95, 0xbfb8aa3b, v87
	v_exp_f32_e32 v94, v94
	v_exp_f32_e32 v95, v95
	v_add_f32_e32 v94, 1.0, v94
	v_add_f32_e32 v95, 1.0, v95
	v_rcp_f32_e32 v94, v94
	v_rcp_f32_e32 v95, v95
	s_nop 0
	v_pk_mul_f32 v[86:87], v[86:87], v[94:95]
	s_nop 0
	v_pk_mul_f32 v[86:87], v[86:87], v[82:83]
	v_mul_f32_e32 v82, 0xbfb8aa3b, v88
	v_mul_f32_e32 v83, 0xbfb8aa3b, v89
	v_exp_f32_e32 v82, v82
	v_exp_f32_e32 v83, v83
	v_add_f32_e32 v82, 1.0, v82
	v_add_f32_e32 v83, 1.0, v83
	v_rcp_f32_e32 v82, v82
	v_rcp_f32_e32 v83, v83
	s_nop 0
	v_pk_mul_f32 v[82:83], v[88:89], v[82:83]
	s_nop 0
	v_pk_mul_f32 v[88:89], v[82:83], v[84:85]
	v_cvt_pk_bf16_f32 v84, v86, v87
	v_cvt_pk_bf16_f32 v82, v90, v91
	v_cvt_pk_bf16_f32 v83, v92, v93
	v_cvt_pk_bf16_f32 v85, v88, v89
	v_add_u32_e32 v86, 0x2c000, v114
	global_store_dwordx4 v86, v[82:85], s[20:21]
	s_nop 1
	v_mul_f32_e32 v82, 0xbfb8aa3b, v78
	v_mul_f32_e32 v83, 0xbfb8aa3b, v79
	v_exp_f32_e32 v82, v82
	v_exp_f32_e32 v83, v83
	v_add_f32_e32 v82, 1.0, v82
	v_add_f32_e32 v83, 1.0, v83
	v_rcp_f32_e32 v82, v82
	v_rcp_f32_e32 v83, v83
	s_nop 0
	v_pk_mul_f32 v[78:79], v[78:79], v[82:83]
	s_nop 0
	v_pk_mul_f32 v[74:75], v[78:79], v[74:75]
	v_mul_f32_e32 v78, 0xbfb8aa3b, v80
	v_mul_f32_e32 v79, 0xbfb8aa3b, v81
	v_exp_f32_e32 v78, v78
	v_exp_f32_e32 v79, v79
	v_add_f32_e32 v78, 1.0, v78
	v_add_f32_e32 v79, 1.0, v79
	v_rcp_f32_e32 v78, v78
	v_rcp_f32_e32 v79, v79
	s_nop 0
	v_pk_mul_f32 v[78:79], v[80:81], v[78:79]
	s_nop 0
	v_pk_mul_f32 v[76:77], v[78:79], v[76:77]
	v_mul_f32_e32 v78, 0xbfb8aa3b, v70
	v_mul_f32_e32 v79, 0xbfb8aa3b, v71
	v_exp_f32_e32 v78, v78
	v_exp_f32_e32 v79, v79
	v_add_f32_e32 v78, 1.0, v78
	v_add_f32_e32 v79, 1.0, v79
	v_rcp_f32_e32 v78, v78
	v_rcp_f32_e32 v79, v79
	s_nop 0
	v_pk_mul_f32 v[70:71], v[70:71], v[78:79]
	s_nop 0
	v_pk_mul_f32 v[70:71], v[70:71], v[66:67]
	v_mul_f32_e32 v66, 0xbfb8aa3b, v72
	v_mul_f32_e32 v67, 0xbfb8aa3b, v73
	v_exp_f32_e32 v66, v66
	v_exp_f32_e32 v67, v67
	v_add_f32_e32 v66, 1.0, v66
	v_add_f32_e32 v67, 1.0, v67
	v_rcp_f32_e32 v66, v66
	v_rcp_f32_e32 v67, v67
	s_nop 0
	v_pk_mul_f32 v[66:67], v[72:73], v[66:67]
	s_nop 0
	v_pk_mul_f32 v[72:73], v[66:67], v[68:69]
	v_cvt_pk_bf16_f32 v68, v70, v71
	v_cvt_pk_bf16_f32 v66, v74, v75
	v_cvt_pk_bf16_f32 v67, v76, v77
	v_cvt_pk_bf16_f32 v69, v72, v73
	v_add_u32_e32 v70, 0x42000, v114
	global_store_dwordx4 v70, v[66:69], s[20:21]
	s_nop 1
	v_mul_f32_e32 v66, 0xbfb8aa3b, v62
	v_mul_f32_e32 v67, 0xbfb8aa3b, v63
	v_exp_f32_e32 v66, v66
	v_exp_f32_e32 v67, v67
	v_add_f32_e32 v66, 1.0, v66
	v_add_f32_e32 v67, 1.0, v67
	v_rcp_f32_e32 v66, v66
	v_rcp_f32_e32 v67, v67
	s_nop 0
	v_pk_mul_f32 v[62:63], v[62:63], v[66:67]
	s_nop 0
	v_pk_mul_f32 v[58:59], v[62:63], v[58:59]
	v_mul_f32_e32 v62, 0xbfb8aa3b, v64
	v_mul_f32_e32 v63, 0xbfb8aa3b, v65
	v_exp_f32_e32 v62, v62
	v_exp_f32_e32 v63, v63
	v_add_f32_e32 v62, 1.0, v62
	v_add_f32_e32 v63, 1.0, v63
	v_rcp_f32_e32 v62, v62
	v_rcp_f32_e32 v63, v63
	s_nop 0
	v_pk_mul_f32 v[62:63], v[64:65], v[62:63]
	s_nop 0
	v_pk_mul_f32 v[60:61], v[62:63], v[60:61]
	v_mul_f32_e32 v62, 0xbfb8aa3b, v54
	v_mul_f32_e32 v63, 0xbfb8aa3b, v55
	v_exp_f32_e32 v62, v62
; __device__ __forceinline__ float siluf_(float x) { return x * sigmoidf_(x); }
; __device__ __forceinline__ u32x4 pack8(const f32x4 a, const f32x4 b) { u32x4 w; w.x = cvt_pk_bf16(a[0], a[1]); w.y = cvt_pk_bf16(a[2], a[3]); w.z = cvt_pk_bf16(b[0], b[1]); w.w = cvt_pk_bf16(b[2], b[3]); return w; }
;     __device__ __forceinline__ void operator()(const Acc& acc, const Unit& u, int wr, int wc, int fr, int fq, const RsPre& pr) const {
;         asm volatile("" : "+v"(fr), "+v"(fq));
;         const int row0 = u.pm * 256 + wr * 64 + fr, col0 = u.pn * 128 + wc * 32 + 8 * fq;
;         const float (&rs)[2][4] = pr.rs;
; #pragma unroll
;         for (int ai = 0; ai < 2; ++ai)
; #pragma unroll
;             for (int m = 0; m < 4; ++m) { f32x4 o[2];
; #pragma unroll
;                 for (int n = 0; n < 2; ++n) { const f32x4 a1 = acc[ai][0][m][n] * rs[ai][m], a3 = acc[ai][1][m][n] * rs[ai][m];
;                     o[n] = (f32x4){siluf_(a1[0]) * a3[0], siluf_(a1[1]) * a3[1], siluf_(a1[2]) * a3[2], siluf_(a1[3]) * a3[3]}; }
;                 *(u32x4*)(ff + (size_t)(row0 + ai * 128 + m * 16) * DFF + col0) = pack8(o[0], o[1]); }
	v_exp_f32_e32 v63, v63
	v_add_f32_e32 v62, 1.0, v62
	v_add_f32_e32 v63, 1.0, v63
	v_rcp_f32_e32 v62, v62
	v_rcp_f32_e32 v63, v63
	s_nop 0
	v_pk_mul_f32 v[54:55], v[54:55], v[62:63]
	s_nop 0
	v_pk_mul_f32 v[54:55], v[54:55], v[50:51]
	v_mul_f32_e32 v50, 0xbfb8aa3b, v56
	v_mul_f32_e32 v51, 0xbfb8aa3b, v57
	v_exp_f32_e32 v50, v50
	v_exp_f32_e32 v51, v51
	v_add_f32_e32 v50, 1.0, v50
	v_add_f32_e32 v51, 1.0, v51
	v_rcp_f32_e32 v50, v50
	v_rcp_f32_e32 v51, v51
	s_nop 0
	v_pk_mul_f32 v[50:51], v[56:57], v[50:51]
	s_nop 0
	v_pk_mul_f32 v[56:57], v[50:51], v[52:53]
	v_cvt_pk_bf16_f32 v52, v54, v55
	v_cvt_pk_bf16_f32 v50, v58, v59
	v_cvt_pk_bf16_f32 v51, v60, v61
	v_cvt_pk_bf16_f32 v53, v56, v57
	v_add_u32_e32 v54, 0xb0000, v114
	global_store_dwordx4 v54, v[50:53], s[20:21]
	s_nop 1
	v_mul_f32_e32 v50, 0xbfb8aa3b, v46
	v_mul_f32_e32 v51, 0xbfb8aa3b, v47
	v_exp_f32_e32 v50, v50
	v_exp_f32_e32 v51, v51
	v_add_f32_e32 v50, 1.0, v50
	v_add_f32_e32 v51, 1.0, v51
	v_rcp_f32_e32 v50, v50
	v_rcp_f32_e32 v51, v51
	s_nop 0
	v_pk_mul_f32 v[46:47], v[46:47], v[50:51]
	s_nop 0
	v_pk_mul_f32 v[42:43], v[46:47], v[42:43]
	v_mul_f32_e32 v46, 0xbfb8aa3b, v48
	v_mul_f32_e32 v47, 0xbfb8aa3b, v49
	v_exp_f32_e32 v46, v46
	v_exp_f32_e32 v47, v47
	v_add_f32_e32 v46, 1.0, v46
	v_add_f32_e32 v47, 1.0, v47
	v_rcp_f32_e32 v46, v46
	v_rcp_f32_e32 v47, v47
	s_nop 0
	v_pk_mul_f32 v[46:47], v[48:49], v[46:47]
	s_nop 0
	v_pk_mul_f32 v[44:45], v[46:47], v[44:45]
	v_mul_f32_e32 v46, 0xbfb8aa3b, v38
	v_mul_f32_e32 v47, 0xbfb8aa3b, v39
	v_exp_f32_e32 v46, v46
	v_exp_f32_e32 v47, v47
	v_add_f32_e32 v46, 1.0, v46
	v_add_f32_e32 v47, 1.0, v47
	v_rcp_f32_e32 v46, v46
	v_rcp_f32_e32 v47, v47
	s_nop 0
	v_pk_mul_f32 v[38:39], v[38:39], v[46:47]
	s_nop 0
	v_pk_mul_f32 v[38:39], v[38:39], v[34:35]
	v_mul_f32_e32 v34, 0xbfb8aa3b, v40
	v_mul_f32_e32 v35, 0xbfb8aa3b, v41
	v_exp_f32_e32 v34, v34
	v_exp_f32_e32 v35, v35
	v_add_f32_e32 v34, 1.0, v34
	v_add_f32_e32 v35, 1.0, v35
	v_rcp_f32_e32 v34, v34
	v_rcp_f32_e32 v35, v35
	s_nop 0
	v_pk_mul_f32 v[34:35], v[40:41], v[34:35]
	s_nop 0
	v_pk_mul_f32 v[40:41], v[34:35], v[36:37]
	v_cvt_pk_bf16_f32 v36, v38, v39
	v_cvt_pk_bf16_f32 v34, v42, v43
	v_cvt_pk_bf16_f32 v35, v44, v45
	v_cvt_pk_bf16_f32 v37, v40, v41
	v_add_u32_e32 v38, 0xc6000, v114
	global_store_dwordx4 v38, v[34:37], s[20:21]
	s_nop 1
	v_mul_f32_e32 v34, 0xbfb8aa3b, v30
	v_mul_f32_e32 v35, 0xbfb8aa3b, v31
	v_exp_f32_e32 v34, v34
	v_exp_f32_e32 v35, v35
	v_add_f32_e32 v34, 1.0, v34
	v_add_f32_e32 v35, 1.0, v35
	v_rcp_f32_e32 v34, v34
	v_rcp_f32_e32 v35, v35
	s_nop 0
	v_pk_mul_f32 v[30:31], v[30:31], v[34:35]
	s_nop 0
	v_pk_mul_f32 v[26:27], v[30:31], v[26:27]
	v_mul_f32_e32 v30, 0xbfb8aa3b, v32
	v_mul_f32_e32 v31, 0xbfb8aa3b, v33
	v_exp_f32_e32 v30, v30
	v_exp_f32_e32 v31, v31
	v_add_f32_e32 v30, 1.0, v30
	v_add_f32_e32 v31, 1.0, v31
	v_rcp_f32_e32 v30, v30
	v_rcp_f32_e32 v31, v31
	s_nop 0
	v_pk_mul_f32 v[30:31], v[32:33], v[30:31]
	s_nop 0
	v_pk_mul_f32 v[28:29], v[30:31], v[28:29]
	v_mul_f32_e32 v30, 0xbfb8aa3b, v22
	v_mul_f32_e32 v31, 0xbfb8aa3b, v23
	v_exp_f32_e32 v30, v30
	v_exp_f32_e32 v31, v31
	v_add_f32_e32 v30, 1.0, v30
	v_add_f32_e32 v31, 1.0, v31
	v_rcp_f32_e32 v30, v30
	v_rcp_f32_e32 v31, v31
	s_nop 0
	v_pk_mul_f32 v[22:23], v[22:23], v[30:31]
	s_nop 0
	v_pk_mul_f32 v[22:23], v[22:23], v[18:19]
	v_mul_f32_e32 v18, 0xbfb8aa3b, v24
	v_mul_f32_e32 v19, 0xbfb8aa3b, v25
	v_exp_f32_e32 v18, v18
	v_exp_f32_e32 v19, v19
	v_add_f32_e32 v18, 1.0, v18
	v_add_f32_e32 v19, 1.0, v19
	v_rcp_f32_e32 v18, v18
	v_rcp_f32_e32 v19, v19
	s_nop 0
	v_pk_mul_f32 v[18:19], v[24:25], v[18:19]
	s_nop 0
	v_pk_mul_f32 v[24:25], v[18:19], v[20:21]
	v_cvt_pk_bf16_f32 v20, v22, v23
	v_cvt_pk_bf16_f32 v18, v26, v27
	v_cvt_pk_bf16_f32 v19, v28, v29
	v_cvt_pk_bf16_f32 v21, v24, v25
	v_add_u32_e32 v22, 0xdc000, v114
	global_store_dwordx4 v22, v[18:21], s[20:21]
	s_nop 1
	v_mul_f32_e32 v18, 0xbfb8aa3b, v14
	v_mul_f32_e32 v19, 0xbfb8aa3b, v15
	v_exp_f32_e32 v18, v18
	v_exp_f32_e32 v19, v19
	v_add_f32_e32 v18, 1.0, v18
	v_add_f32_e32 v19, 1.0, v19
	v_rcp_f32_e32 v18, v18
	v_rcp_f32_e32 v19, v19
	s_nop 0
	v_pk_mul_f32 v[14:15], v[14:15], v[18:19]
	s_nop 0
	v_pk_mul_f32 v[10:11], v[14:15], v[10:11]
	v_mul_f32_e32 v14, 0xbfb8aa3b, v16
	v_mul_f32_e32 v15, 0xbfb8aa3b, v17
	v_exp_f32_e32 v14, v14
	v_exp_f32_e32 v15, v15
; __device__ __forceinline__ float siluf_(float x) { return x * sigmoidf_(x); }
; __device__ __forceinline__ u32x4 pack8(const f32x4 a, const f32x4 b) { u32x4 w; w.x = cvt_pk_bf16(a[0], a[1]); w.y = cvt_pk_bf16(a[2], a[3]); w.z = cvt_pk_bf16(b[0], b[1]); w.w = cvt_pk_bf16(b[2], b[3]); return w; }
; template <class Epi>
; __device__ __forceinline__ void gemm_phase(LAS unsigned char* lds, const Gemm g, const StaticOrder& S, const Epi& E) {
;     ...
;         if (!(Epi::PAIRS && cur.alt == 0)) {
; #pragma unroll
;         for (int a = 0; a < 2; ++a)
; #pragma unroll
;             for (int b = 0; b < 2; ++b)
; #pragma unroll
;                 for (int m = 0; m < 4; ++m)
; #pragma unroll
;                     for (int n = 0; n < 2; ++n) acc[a][b][m][n] = (f32x4){0.f, 0.f, 0.f, 0.f}; }
;     __device__ __forceinline__ void operator()(const Acc& acc, const Unit& u, int wr, int wc, int fr, int fq, const RsPre& pr) const {
;         asm volatile("" : "+v"(fr), "+v"(fq));
;         const int row0 = u.pm * 256 + wr * 64 + fr, col0 = u.pn * 128 + wc * 32 + 8 * fq;
;         const float (&rs)[2][4] = pr.rs;
; #pragma unroll
;         for (int ai = 0; ai < 2; ++ai)
; #pragma unroll
;             for (int m = 0; m < 4; ++m) { f32x4 o[2];
; #pragma unroll
;                 for (int n = 0; n < 2; ++n) { const f32x4 a1 = acc[ai][0][m][n] * rs[ai][m], a3 = acc[ai][1][m][n] * rs[ai][m];
;                     o[n] = (f32x4){siluf_(a1[0]) * a3[0], siluf_(a1[1]) * a3[1], siluf_(a1[2]) * a3[2], siluf_(a1[3]) * a3[3]}; }
;                 *(u32x4*)(ff + (size_t)(row0 + ai * 128 + m * 16) * DFF + col0) = pack8(o[0], o[1]); }
	v_add_f32_e32 v14, 1.0, v14
	v_add_f32_e32 v15, 1.0, v15
	v_rcp_f32_e32 v14, v14
	v_rcp_f32_e32 v15, v15
	s_nop 0
	v_pk_mul_f32 v[14:15], v[16:17], v[14:15]
	s_nop 0
	v_pk_mul_f32 v[12:13], v[14:15], v[12:13]
	v_mul_f32_e32 v14, 0xbfb8aa3b, v6
	v_mul_f32_e32 v15, 0xbfb8aa3b, v7
	v_exp_f32_e32 v14, v14
	v_exp_f32_e32 v15, v15
	v_add_f32_e32 v14, 1.0, v14
	v_add_f32_e32 v15, 1.0, v15
	v_rcp_f32_e32 v14, v14
	v_rcp_f32_e32 v15, v15
	s_nop 0
	v_pk_mul_f32 v[6:7], v[6:7], v[14:15]
	s_nop 0
	v_pk_mul_f32 v[6:7], v[6:7], v[2:3]
	v_mul_f32_e32 v2, 0xbfb8aa3b, v8
	v_mul_f32_e32 v3, 0xbfb8aa3b, v9
	v_exp_f32_e32 v2, v2
	v_exp_f32_e32 v3, v3
	v_add_f32_e32 v2, 1.0, v2
	v_add_f32_e32 v3, 1.0, v3
	v_rcp_f32_e32 v2, v2
	v_rcp_f32_e32 v3, v3
	s_nop 0
	v_pk_mul_f32 v[2:3], v[8:9], v[2:3]
	s_nop 0
	v_pk_mul_f32 v[8:9], v[2:3], v[4:5]
	v_cvt_pk_bf16_f32 v4, v6, v7
	v_cvt_pk_bf16_f32 v2, v10, v11
	v_cvt_pk_bf16_f32 v3, v12, v13
	v_cvt_pk_bf16_f32 v5, v8, v9
	v_add_u32_e32 v6, 0xf2000, v114
	v_mov_b32_e32 v10, 0
	v_mov_b32_e32 v11, 0
	v_mov_b32_e32 v12, 0
	v_mov_b32_e32 v13, 0
	v_mov_b32_e32 v18, 0
	v_mov_b32_e32 v19, 0
	v_mov_b32_e32 v20, 0
	v_mov_b32_e32 v21, 0
	v_mov_b32_e32 v26, 0
	v_mov_b32_e32 v27, 0
	v_mov_b32_e32 v28, 0
	v_mov_b32_e32 v29, 0
	v_mov_b32_e32 v34, 0
	v_mov_b32_e32 v35, 0
	v_mov_b32_e32 v36, 0
	v_mov_b32_e32 v37, 0
	v_mov_b32_e32 v42, 0
	v_mov_b32_e32 v43, 0
	v_mov_b32_e32 v44, 0
	v_mov_b32_e32 v45, 0
	v_mov_b32_e32 v50, 0
	v_mov_b32_e32 v51, 0
	v_mov_b32_e32 v52, 0
	v_mov_b32_e32 v53, 0
	v_mov_b32_e32 v58, 0
	v_mov_b32_e32 v59, 0
	v_mov_b32_e32 v60, 0
	v_mov_b32_e32 v61, 0
	v_mov_b32_e32 v7, 0
	v_mov_b32_e32 v8, 0
	v_mov_b32_e32 v9, 0
	v_mov_b32_e32 v14, 0
	v_mov_b32_e32 v15, 0
	v_mov_b32_e32 v16, 0
	v_mov_b32_e32 v17, 0
	v_mov_b32_e32 v22, 0
	v_mov_b32_e32 v23, 0
	v_mov_b32_e32 v24, 0
	v_mov_b32_e32 v25, 0
	v_mov_b32_e32 v30, 0
	v_mov_b32_e32 v31, 0
	v_mov_b32_e32 v32, 0
	v_mov_b32_e32 v33, 0
	v_mov_b32_e32 v38, 0
	v_mov_b32_e32 v39, 0
	v_mov_b32_e32 v40, 0
	v_mov_b32_e32 v41, 0
	v_mov_b32_e32 v46, 0
	v_mov_b32_e32 v47, 0
	v_mov_b32_e32 v48, 0
	v_mov_b32_e32 v49, 0
	v_mov_b32_e32 v54, 0
	v_mov_b32_e32 v55, 0
	v_mov_b32_e32 v56, 0
	v_mov_b32_e32 v57, 0
	v_mov_b32_e32 v62, 0
	v_mov_b32_e32 v63, 0
	v_mov_b32_e32 v64, 0
	v_mov_b32_e32 v65, 0
	v_mov_b32_e32 v66, 0
	v_mov_b32_e32 v67, 0
	v_mov_b32_e32 v68, 0
	v_mov_b32_e32 v69, 0
	v_mov_b32_e32 v74, 0
	v_mov_b32_e32 v75, 0
	v_mov_b32_e32 v76, 0
	v_mov_b32_e32 v77, 0
	v_mov_b32_e32 v82, 0
	v_mov_b32_e32 v83, 0
	v_mov_b32_e32 v84, 0
	v_mov_b32_e32 v85, 0
	v_mov_b32_e32 v90, 0
	v_mov_b32_e32 v91, 0
	v_mov_b32_e32 v92, 0
	v_mov_b32_e32 v93, 0
	v_mov_b32_e32 v98, 0
	v_mov_b32_e32 v99, 0
	v_mov_b32_e32 v100, 0
	v_mov_b32_e32 v101, 0
	v_mov_b32_e32 v106, 0
	v_mov_b32_e32 v107, 0
	v_mov_b32_e32 v108, 0
	v_mov_b32_e32 v109, 0
	v_mov_b32_e32 v114, 0
	v_mov_b32_e32 v115, 0
	v_mov_b32_e32 v116, 0
	v_mov_b32_e32 v117, 0
	v_mov_b32_e32 v122, 0
	v_mov_b32_e32 v123, 0
	v_mov_b32_e32 v124, 0
	v_mov_b32_e32 v125, 0
	v_mov_b32_e32 v70, 0
	v_mov_b32_e32 v71, 0
	v_mov_b32_e32 v72, 0
	v_mov_b32_e32 v73, 0
	v_mov_b32_e32 v78, 0
	v_mov_b32_e32 v79, 0
	v_mov_b32_e32 v80, 0
	v_mov_b32_e32 v81, 0
	v_mov_b32_e32 v86, 0
	v_mov_b32_e32 v87, 0
	v_mov_b32_e32 v88, 0
	v_mov_b32_e32 v89, 0
	v_mov_b32_e32 v94, 0
	v_mov_b32_e32 v95, 0
	v_mov_b32_e32 v96, 0
	v_mov_b32_e32 v97, 0
	v_mov_b32_e32 v102, 0
	v_mov_b32_e32 v103, 0
	v_mov_b32_e32 v104, 0
	v_mov_b32_e32 v105, 0
	v_mov_b32_e32 v110, 0
	v_mov_b32_e32 v111, 0
	v_mov_b32_e32 v112, 0
	v_mov_b32_e32 v113, 0
	v_mov_b32_e32 v118, 0
	v_mov_b32_e32 v119, 0
	v_mov_b32_e32 v120, 0
	v_mov_b32_e32 v121, 0
	v_mov_b32_e32 v126, 0
	v_mov_b32_e32 v127, 0
	v_mov_b32_e32 v128, 0
	v_mov_b32_e32 v129, 0
	global_store_dwordx4 v6, v[2:5], s[20:21]
	s_cbranch_vccz .LBB0_96
	s_nop 0
	v_lshl_add_u32 v2, s42, 8, v145
	v_ashrrev_i32_e32 v3, 31, v2
	v_lshl_add_u64 v[2:3], v[2:3], 2, s[4:5]
	global_load_dword v154, v[2:3], off
	global_load_dword v152, v[2:3], off offset:64
	global_load_dword v150, v[2:3], off offset:128
	global_load_dword v148, v[2:3], off offset:192
	global_load_dword v146, v[2:3], off offset:512
	global_load_dword v144, v[2:3], off offset:576
	global_load_dword v142, v[2:3], off offset:640
	global_load_dword v136, v[2:3], off offset:704
	s_mov_b64 s[60:61], 0
	s_branch .LBB0_96

; #define PG8_STAGE(bufoff, gbase, voff) do { _Pragma("unroll") for (int _i = 0; _i < 2; ++_i) \
;         __builtin_amdgcn_global_load_lds((const unsigned*)((const char*)(gbase) + (voff)[_i]), (LAS unsigned*)(lds + (bufoff) + ldsw + _i * 8192), 16, 0, 0); } while (0)
; #define PG8_LDA(dst, b, h) do { _Pragma("unroll") for (int m = 0; m < 4; ++m) _Pragma("unroll") for (int k = 0; k < 2; ++k) dst[m][k] = *(const LAS bf16x8*)(lds + PG8_SA(b, h) + aoff + m * 2048 + k * 1024); } while (0)
; #define PG8_LDB(dst, b, h) do { _Pragma("unroll") for (int n = 0; n < 2; ++n) _Pragma("unroll") for (int k = 0; k < 2; ++k) dst[n][k] = *(const LAS bf16x8*)(lds + PG8_SB(b, h) + boff + n * 2048 + k * 1024); } while (0)
; #define PG8_MMA(ai, bj, At, Bt) do { __builtin_amdgcn_s_setprio(1); _Pragma("unroll") for (int m = 0; m < 4; ++m) _Pragma("unroll") for (int n = 0; n < 2; ++n) _Pragma("unroll") for (int k = 0; k < 2; ++k) \
;         acc[ai][bj][m][n] = __builtin_amdgcn_mfma_f32_16x16x32_bf16(Bt[n][k], At[m][k], acc[ai][bj][m][n], 0, 0, 0); __builtin_amdgcn_s_setprio(0); } while (0)
; #define PG8_WAIT_L(n) asm volatile("s_waitcnt lgkmcnt(" #n ")" ::: "memory")
; #define PG8_BAR __builtin_amdgcn_s_barrier()
; #define PG8_SCHED __builtin_amdgcn_sched_barrier(0)
; template <class Epi>
; __device__ __forceinline__ void gemm_phase(LAS unsigned char* lds, const Gemm g, const StaticOrder& S, const Epi& E) {
;     ...
;         for (int t = 0; t < nt; t += 2) {
;             const bool last = (t == nt - 2);
;             const char* a1 = cA + (size_t)(t + 1) * kstep;
;             const char* a2 = last ? nA : cA + (size_t)(t + 2) * kstep; const char* b2 = last ? nB : cB + (size_t)(t + 2) * kstep;
;             const char* a3 = a2 + kstep; const char* b3 = b2 + kstep;
;             PG8_LDB(B0, 0, 0); PG8_SCHED; PG8_LDA(At, 0, 0); PG8_STAGE(PG8_SA(1, 1), a1 + hA, voffA);
;             PG8_WAIT_L(8); PG8_BAR; PG8_WAIT_L(0); PG8_MMA(0, 0, At, B0); PG8_BAR; PG8_SCHED;
;     ...
;         if (!(Epi::PAIRS && cur.alt == 0)) {
; #pragma unroll
;         for (int a = 0; a < 2; ++a)
; #pragma unroll
;             for (int b = 0; b < 2; ++b)
; #pragma unroll
;                 for (int m = 0; m < 4; ++m)
; #pragma unroll
;                     for (int n = 0; n < 2; ++n) acc[a][b][m][n] = (f32x4){0.f, 0.f, 0.f, 0.f}; }
.LBB0_622:
	v_mov_b64_e32 v[2:3], 0x891
	s_ashr_i32 s23, s22, 31
	v_cmp_lt_i64_e32 vcc, s[40:41], v[2:3]
	s_lshl_b64 s[40:41], s[22:23], 19
	s_add_u32 s40, s36, s40
	s_addc_u32 s41, s37, s41
	s_and_b64 s[42:43], vcc, exec
	s_cselect_b32 s23, s41, s47
	s_cselect_b32 s62, s40, s46
	s_ashr_i32 s15, s14, 31
	s_lshl_b64 s[42:43], s[14:15], 19
	s_add_u32 s42, s8, s42
	s_addc_u32 s43, s9, s43
	s_and_b64 s[50:51], vcc, exec
	s_cselect_b32 s15, s43, s49
	s_cselect_b32 s63, s42, s48
	s_add_u32 s46, s46, 0x40080
	s_addc_u32 s47, s47, 0
	s_add_u32 s64, s48, 0x100
	v_mov_b32_e32 v2, 0
	s_addc_u32 s65, s49, 0
	s_mov_b32 s66, -2
	s_cmp_eq_u32 s61, 1
	s_cbranch_scc1 .Lzf_s1
	v_mov_b32_e32 v3, v2
	v_mov_b32_e32 v4, v2
	v_mov_b32_e32 v5, v2
	v_mov_b32_e32 v18, v2
	s_branch .LBB0_623
.Lzf_s1:
	v_mov_b32_e32 v3, v2
	v_mov_b32_e32 v4, v2
	v_mov_b32_e32 v5, v2
	v_mov_b32_e32 v6, v2
	v_mov_b32_e32 v7, v2
	v_mov_b32_e32 v8, v2
	v_mov_b32_e32 v9, v2
	v_mov_b32_e32 v10, v2
	v_mov_b32_e32 v11, v2
	v_mov_b32_e32 v12, v2
	v_mov_b32_e32 v13, v2
	v_mov_b32_e32 v18, v2
	v_mov_b32_e32 v19, v2
	v_mov_b32_e32 v20, v2
	v_mov_b32_e32 v21, v2
	v_mov_b32_e32 v26, v2
	v_mov_b32_e32 v27, v2
	v_mov_b32_e32 v28, v2
	v_mov_b32_e32 v29, v2
	v_mov_b32_e32 v34, v2
	v_mov_b32_e32 v35, v2
	v_mov_b32_e32 v36, v2
	v_mov_b32_e32 v37, v2
	v_mov_b32_e32 v42, v2
	v_mov_b32_e32 v43, v2
	v_mov_b32_e32 v44, v2
	v_mov_b32_e32 v45, v2
	v_mov_b32_e32 v50, v2
	v_mov_b32_e32 v51, v2
	v_mov_b32_e32 v52, v2
	v_mov_b32_e32 v53, v2
	v_mov_b32_e32 v14, v2
	v_mov_b32_e32 v15, v2
	v_mov_b32_e32 v16, v2
	v_mov_b32_e32 v17, v2
	v_mov_b32_e32 v22, v2
	v_mov_b32_e32 v23, v2
	v_mov_b32_e32 v24, v2
	v_mov_b32_e32 v25, v2
	v_mov_b32_e32 v30, v2
	v_mov_b32_e32 v31, v2
	v_mov_b32_e32 v32, v2
	v_mov_b32_e32 v33, v2
	v_mov_b32_e32 v38, v2
	v_mov_b32_e32 v39, v2
	v_mov_b32_e32 v40, v2
	v_mov_b32_e32 v41, v2
	v_mov_b32_e32 v46, v2
	v_mov_b32_e32 v47, v2
	v_mov_b32_e32 v48, v2
	v_mov_b32_e32 v49, v2
	v_mov_b32_e32 v54, v2
	v_mov_b32_e32 v55, v2
	v_mov_b32_e32 v56, v2
	v_mov_b32_e32 v57, v2
	v_mov_b32_e32 v58, v2
	v_mov_b32_e32 v59, v2
	v_mov_b32_e32 v60, v2
	v_mov_b32_e32 v61, v2
	v_mov_b32_e32 v62, v2
	v_mov_b32_e32 v63, v2
	v_mov_b32_e32 v64, v2
	v_mov_b32_e32 v65, v2
	v_mov_b32_e32 v66, v2
	v_mov_b32_e32 v67, v2
	v_mov_b32_e32 v68, v2
	v_mov_b32_e32 v69, v2
	v_mov_b32_e32 v70, v2
	v_mov_b32_e32 v71, v2
	v_mov_b32_e32 v72, v2
	v_mov_b32_e32 v73, v2
	v_mov_b32_e32 v74, v2
	v_mov_b32_e32 v75, v2
	v_mov_b32_e32 v76, v2
	v_mov_b32_e32 v77, v2
	v_mov_b32_e32 v82, v2
	v_mov_b32_e32 v83, v2
	v_mov_b32_e32 v84, v2
	v_mov_b32_e32 v85, v2
	v_mov_b32_e32 v90, v2
	v_mov_b32_e32 v91, v2
	v_mov_b32_e32 v92, v2
	v_mov_b32_e32 v93, v2
	v_mov_b32_e32 v98, v2
	v_mov_b32_e32 v99, v2
	v_mov_b32_e32 v100, v2
	v_mov_b32_e32 v101, v2
	v_mov_b32_e32 v106, v2
	v_mov_b32_e32 v107, v2
	v_mov_b32_e32 v108, v2
	v_mov_b32_e32 v109, v2
	v_mov_b32_e32 v114, v2
	v_mov_b32_e32 v115, v2
	v_mov_b32_e32 v116, v2
	v_mov_b32_e32 v117, v2
	v_mov_b32_e32 v78, v2
	v_mov_b32_e32 v79, v2
	v_mov_b32_e32 v80, v2
	v_mov_b32_e32 v81, v2
	v_mov_b32_e32 v86, v2
	v_mov_b32_e32 v87, v2
	v_mov_b32_e32 v88, v2
	v_mov_b32_e32 v89, v2
	v_mov_b32_e32 v94, v2
	v_mov_b32_e32 v95, v2
	v_mov_b32_e32 v96, v2
	v_mov_b32_e32 v97, v2
	v_mov_b32_e32 v102, v2
	v_mov_b32_e32 v103, v2
	v_mov_b32_e32 v104, v2
	v_mov_b32_e32 v105, v2
	v_mov_b32_e32 v110, v2
	v_mov_b32_e32 v111, v2
	v_mov_b32_e32 v112, v2
	v_mov_b32_e32 v113, v2
	v_mov_b32_e32 v118, v2
	v_mov_b32_e32 v119, v2
	v_mov_b32_e32 v120, v2
	v_mov_b32_e32 v121, v2
	v_mov_b32_e32 v122, v2
	v_mov_b32_e32 v123, v2
	v_mov_b32_e32 v124, v2
	v_mov_b32_e32 v125, v2
	v_mov_b32_e32 v126, v2
	v_mov_b32_e32 v127, v2
	v_mov_b32_e32 v128, v2
	v_mov_b32_e32 v129, v2
.LBB0_623:
	s_add_u32 s48, s46, 0xfffc0080
	s_addc_u32 s49, s47, -1
	s_add_i32 s67, 0, 0x10000
	v_add_u32_e32 v151, s67, v143
	ds_read_b128 v[156:159], v151
	ds_read_b128 v[160:163], v151 offset:1024
	ds_read_b128 v[164:167], v151 offset:2048
	ds_read_b128 v[168:171], v151 offset:3072
	s_cmp_eq_u32 s66, 12
	s_cselect_b32 s51, s23, s49
	s_cselect_b32 s50, s62, s48
	s_cselect_b32 s49, s15, s65
	s_cselect_b32 s48, s63, s64
	s_add_i32 m0, s53, 0xc000
	ds_read_b128 v[172:175], v149
	ds_read_b128 v[176:179], v149 offset:1024
	ds_read_b128 v[180:183], v149 offset:2048
	ds_read_b128 v[184:187], v149 offset:3072
	ds_read_b128 v[188:191], v149 offset:4096
	ds_read_b128 v[192:195], v149 offset:5120
	ds_read_b128 v[202:205], v149 offset:6144
	ds_read_b128 v[206:209], v149 offset:7168
	global_load_lds_dwordx4 v144, s[46:47]
	s_add_i32 m0, s53, 0xe000
	s_nop 0
	global_load_lds_dwordx4 v146, s[46:47]
	s_waitcnt lgkmcnt(8)
	s_barrier
	s_waitcnt lgkmcnt(0)
	s_setprio 1
	s_waitcnt lgkmcnt(0)
	v_mfma_f32_16x16x32_bf16 v[126:129], v[156:159], v[172:175], v[126:129]
	v_mfma_f32_16x16x32_bf16 v[122:125], v[164:167], v[172:175], v[122:125]
	v_mfma_f32_16x16x32_bf16 v[118:121], v[156:159], v[180:183], v[118:121]
	v_mfma_f32_16x16x32_bf16 v[110:113], v[164:167], v[180:183], v[110:113]
	v_mfma_f32_16x16x32_bf16 v[102:105], v[156:159], v[188:191], v[102:105]
	v_mfma_f32_16x16x32_bf16 v[94:97], v[164:167], v[188:191], v[94:97]
	v_mfma_f32_16x16x32_bf16 v[86:89], v[156:159], v[202:205], v[86:89]
	v_mfma_f32_16x16x32_bf16 v[78:81], v[164:167], v[202:205], v[78:81]
	v_mfma_f32_16x16x32_bf16 v[126:129], v[160:163], v[176:179], v[126:129]
	v_mfma_f32_16x16x32_bf16 v[122:125], v[168:171], v[176:179], v[122:125]
	v_mfma_f32_16x16x32_bf16 v[118:121], v[160:163], v[184:187], v[118:121]
	v_mfma_f32_16x16x32_bf16 v[110:113], v[168:171], v[184:187], v[110:113]
	v_mfma_f32_16x16x32_bf16 v[102:105], v[160:163], v[192:195], v[102:105]
	v_mfma_f32_16x16x32_bf16 v[94:97], v[168:171], v[192:195], v[94:97]
	v_mfma_f32_16x16x32_bf16 v[86:89], v[160:163], v[206:209], v[86:89]
	v_mfma_f32_16x16x32_bf16 v[78:81], v[168:171], v[206:209], v[78:81]
	s_setprio 0
	s_barrier
; #define PG8_STAGE(bufoff, gbase, voff) do { _Pragma("unroll") for (int _i = 0; _i < 2; ++_i) \
;         __builtin_amdgcn_global_load_lds((const unsigned*)((const char*)(gbase) + (voff)[_i]), (LAS unsigned*)(lds + (bufoff) + ldsw + _i * 8192), 16, 0, 0); } while (0)
; #define PG8_LDA(dst, b, h) do { _Pragma("unroll") for (int m = 0; m < 4; ++m) _Pragma("unroll") for (int k = 0; k < 2; ++k) dst[m][k] = *(const LAS bf16x8*)(lds + PG8_SA(b, h) + aoff + m * 2048 + k * 1024); } while (0)
; #define PG8_LDB(dst, b, h) do { _Pragma("unroll") for (int n = 0; n < 2; ++n) _Pragma("unroll") for (int k = 0; k < 2; ++k) dst[n][k] = *(const LAS bf16x8*)(lds + PG8_SB(b, h) + boff + n * 2048 + k * 1024); } while (0)
; #define PG8_MMA(ai, bj, At, Bt) do { __builtin_amdgcn_s_setprio(1); _Pragma("unroll") for (int m = 0; m < 4; ++m) _Pragma("unroll") for (int n = 0; n < 2; ++n) _Pragma("unroll") for (int k = 0; k < 2; ++k) \
;         acc[ai][bj][m][n] = __builtin_amdgcn_mfma_f32_16x16x32_bf16(Bt[n][k], At[m][k], acc[ai][bj][m][n], 0, 0, 0); __builtin_amdgcn_s_setprio(0); } while (0)
; #define PG8_WAIT_V(n) asm volatile("s_waitcnt vmcnt(" #n ")" ::: "memory")
; #define PG8_WAIT_L(n) asm volatile("s_waitcnt lgkmcnt(" #n ")" ::: "memory")
; #define PG8_BAR __builtin_amdgcn_s_barrier()
; #define PG8_SCHED __builtin_amdgcn_sched_barrier(0)
; template <class Epi>
; __device__ __forceinline__ void gemm_phase(LAS unsigned char* lds, const Gemm g, const StaticOrder& S, const Epi& E) {
;     ...
;             PG8_LDB(B1, 0, 1); PG8_STAGE(PG8_SB(0, 0), b2, voffB);
;             PG8_BAR; PG8_WAIT_L(0); PG8_MMA(0, 1, At, B1); PG8_BAR;
;             PG8_LDA(At, 0, 1); PG8_STAGE(PG8_SA(0, 0), a2, voffA);
;             PG8_BAR; PG8_WAIT_L(0); PG8_MMA(1, 0, At, B0); PG8_BAR; PG8_SCHED;
;             PG8_STAGE(PG8_SB(0, 1), b2 + hB, voffB);
;             PG8_WAIT_V(6); PG8_BAR; PG8_MMA(1, 1, At, B1); PG8_BAR;
;             PG8_LDB(B0, 1, 0); PG8_SCHED; PG8_LDA(At, 1, 0); PG8_STAGE(PG8_SA(0, 1), a2 + hA, voffA);
;             PG8_WAIT_L(8); PG8_BAR; PG8_WAIT_L(0); PG8_MMA(0, 0, At, B0); PG8_BAR; PG8_SCHED;
;             PG8_LDB(B1, 1, 1); PG8_STAGE(PG8_SB(1, 0), b3, voffB);
;             PG8_BAR; PG8_WAIT_L(0); PG8_MMA(0, 1, At, B1); PG8_BAR;
;             PG8_LDA(At, 1, 1); PG8_STAGE(PG8_SA(1, 0), a3, voffA);
	s_add_i32 s70, 0, 0x14000
	s_add_i32 s67, s67, s33
	v_add_u32_e32 v151, s70, v143
	s_mov_b32 m0, s67
	ds_read_b128 v[210:213], v151
	ds_read_b128 v[214:217], v151 offset:1024
	ds_read_b128 v[218:221], v151 offset:2048
	ds_read_b128 v[222:225], v151 offset:3072
	global_load_lds_dwordx4 v0, s[48:49]
	s_add_i32 m0, s67, 0x2000
	s_nop 0
	global_load_lds_dwordx4 v134, s[48:49]
	s_barrier
	s_waitcnt lgkmcnt(0)
	s_setprio 1
	s_waitcnt lgkmcnt(0)
	v_mfma_f32_16x16x32_bf16 v[114:117], v[210:213], v[172:175], v[114:117]
	v_mfma_f32_16x16x32_bf16 v[106:109], v[218:221], v[172:175], v[106:109]
	v_mfma_f32_16x16x32_bf16 v[98:101], v[210:213], v[180:183], v[98:101]
	v_mfma_f32_16x16x32_bf16 v[90:93], v[218:221], v[180:183], v[90:93]
	v_mfma_f32_16x16x32_bf16 v[82:85], v[210:213], v[188:191], v[82:85]
	v_mfma_f32_16x16x32_bf16 v[74:77], v[218:221], v[188:191], v[74:77]
	v_mfma_f32_16x16x32_bf16 v[70:73], v[210:213], v[202:205], v[70:73]
	v_mfma_f32_16x16x32_bf16 v[66:69], v[218:221], v[202:205], v[66:69]
	v_mfma_f32_16x16x32_bf16 v[114:117], v[214:217], v[176:179], v[114:117]
	v_mfma_f32_16x16x32_bf16 v[106:109], v[222:225], v[176:179], v[106:109]
	v_mfma_f32_16x16x32_bf16 v[98:101], v[214:217], v[184:187], v[98:101]
	v_mfma_f32_16x16x32_bf16 v[90:93], v[222:225], v[184:187], v[90:93]
	v_mfma_f32_16x16x32_bf16 v[82:85], v[214:217], v[192:195], v[82:85]
	v_mfma_f32_16x16x32_bf16 v[74:77], v[222:225], v[192:195], v[74:77]
	v_mfma_f32_16x16x32_bf16 v[70:73], v[214:217], v[206:209], v[70:73]
	v_mfma_f32_16x16x32_bf16 v[66:69], v[222:225], v[206:209], v[66:69]
	s_setprio 0
	s_mov_b32 m0, s53
	s_barrier
	ds_read_b128 v[172:175], v149 offset:16384
	ds_read_b128 v[176:179], v149 offset:17408
	ds_read_b128 v[180:183], v149 offset:18432
	ds_read_b128 v[184:187], v149 offset:19456
	ds_read_b128 v[188:191], v149 offset:20480
	ds_read_b128 v[192:195], v149 offset:21504
	ds_read_b128 v[202:205], v149 offset:22528
	ds_read_b128 v[206:209], v149 offset:23552
	global_load_lds_dwordx4 v130, s[50:51]
	s_mov_b32 m0, s54
	s_nop 0
	global_load_lds_dwordx4 v132, s[50:51]
	s_barrier
	s_waitcnt lgkmcnt(0)
	s_setprio 1
	s_waitcnt lgkmcnt(0)
	v_mfma_f32_16x16x32_bf16 v[62:65], v[156:159], v[172:175], v[62:65]
	v_mfma_f32_16x16x32_bf16 v[58:61], v[164:167], v[172:175], v[58:61]
	v_mfma_f32_16x16x32_bf16 v[54:57], v[156:159], v[180:183], v[54:57]
	v_mfma_f32_16x16x32_bf16 v[46:49], v[164:167], v[180:183], v[46:49]
	v_mfma_f32_16x16x32_bf16 v[38:41], v[156:159], v[188:191], v[38:41]
	v_mfma_f32_16x16x32_bf16 v[30:33], v[164:167], v[188:191], v[30:33]
	v_mfma_f32_16x16x32_bf16 v[22:25], v[156:159], v[202:205], v[22:25]
	v_mfma_f32_16x16x32_bf16 v[14:17], v[164:167], v[202:205], v[14:17]
	v_mfma_f32_16x16x32_bf16 v[62:65], v[160:163], v[176:179], v[62:65]
	v_mfma_f32_16x16x32_bf16 v[58:61], v[168:171], v[176:179], v[58:61]
	v_mfma_f32_16x16x32_bf16 v[54:57], v[160:163], v[184:187], v[54:57]
	v_mfma_f32_16x16x32_bf16 v[46:49], v[168:171], v[184:187], v[46:49]
	v_mfma_f32_16x16x32_bf16 v[38:41], v[160:163], v[192:195], v[38:41]
	v_mfma_f32_16x16x32_bf16 v[30:33], v[168:171], v[192:195], v[30:33]
	v_mfma_f32_16x16x32_bf16 v[22:25], v[160:163], v[206:209], v[22:25]
	v_mfma_f32_16x16x32_bf16 v[14:17], v[168:171], v[206:209], v[14:17]
	s_setprio 0
	s_barrier
	s_add_u32 s68, s48, 0x40000
	s_addc_u32 s69, s49, 0
	s_add_i32 s67, s70, s33
	s_mov_b32 m0, s67
	s_nop 0
	global_load_lds_dwordx4 v0, s[68:69]
	s_add_i32 m0, s67, 0x2000
	s_nop 0
	global_load_lds_dwordx4 v134, s[68:69]
	s_waitcnt vmcnt(6)
	s_barrier
	s_setprio 1
	v_mfma_f32_16x16x32_bf16 v[50:53], v[210:213], v[172:175], v[50:53]
	v_mfma_f32_16x16x32_bf16 v[42:45], v[218:221], v[172:175], v[42:45]
	v_mfma_f32_16x16x32_bf16 v[34:37], v[210:213], v[180:183], v[34:37]
	v_mfma_f32_16x16x32_bf16 v[26:29], v[218:221], v[180:183], v[26:29]
	v_mfma_f32_16x16x32_bf16 v[18:21], v[210:213], v[188:191], v[18:21]
	v_mfma_f32_16x16x32_bf16 v[10:13], v[218:221], v[188:191], v[10:13]
	v_mfma_f32_16x16x32_bf16 v[6:9], v[210:213], v[202:205], v[6:9]
	v_mfma_f32_16x16x32_bf16 v[2:5], v[218:221], v[202:205], v[2:5]
	v_mfma_f32_16x16x32_bf16 v[50:53], v[214:217], v[176:179], v[50:53]
	v_mfma_f32_16x16x32_bf16 v[42:45], v[222:225], v[176:179], v[42:45]
	v_mfma_f32_16x16x32_bf16 v[34:37], v[214:217], v[184:187], v[34:37]
	v_mfma_f32_16x16x32_bf16 v[26:29], v[222:225], v[184:187], v[26:29]
	v_mfma_f32_16x16x32_bf16 v[18:21], v[214:217], v[192:195], v[18:21]
	v_mfma_f32_16x16x32_bf16 v[10:13], v[222:225], v[192:195], v[10:13]
	v_mfma_f32_16x16x32_bf16 v[6:9], v[214:217], v[206:209], v[6:9]
	v_mfma_f32_16x16x32_bf16 v[2:5], v[222:225], v[206:209], v[2:5]
	s_setprio 0
	s_add_i32 s67, 0, 0x18000
	v_add_u32_e32 v151, s67, v143
	s_barrier
	ds_read_b128 v[156:159], v151
	ds_read_b128 v[160:163], v151 offset:1024
	ds_read_b128 v[164:167], v151 offset:2048
	ds_read_b128 v[168:171], v151 offset:3072
	s_add_u32 s68, s50, 0x40000
	s_addc_u32 s69, s51, 0
	s_mov_b32 m0, s55
	ds_read_b128 v[172:175], v149 offset:32768
	ds_read_b128 v[176:179], v149 offset:33792
	ds_read_b128 v[180:183], v149 offset:34816
	ds_read_b128 v[184:187], v149 offset:35840
	ds_read_b128 v[188:191], v149 offset:36864
	ds_read_b128 v[192:195], v149 offset:37888
	ds_read_b128 v[202:205], v149 offset:38912
	ds_read_b128 v[206:209], v149 offset:39936
	global_load_lds_dwordx4 v130, s[68:69]
	s_mov_b32 m0, s56
	s_nop 0
	global_load_lds_dwordx4 v132, s[68:69]
	s_waitcnt lgkmcnt(8)
	s_barrier
; #define PG8_STAGE(bufoff, gbase, voff) do { _Pragma("unroll") for (int _i = 0; _i < 2; ++_i) \
;         __builtin_amdgcn_global_load_lds((const unsigned*)((const char*)(gbase) + (voff)[_i]), (LAS unsigned*)(lds + (bufoff) + ldsw + _i * 8192), 16, 0, 0); } while (0)
; #define PG8_LDA(dst, b, h) do { _Pragma("unroll") for (int m = 0; m < 4; ++m) _Pragma("unroll") for (int k = 0; k < 2; ++k) dst[m][k] = *(const LAS bf16x8*)(lds + PG8_SA(b, h) + aoff + m * 2048 + k * 1024); } while (0)
; #define PG8_LDB(dst, b, h) do { _Pragma("unroll") for (int n = 0; n < 2; ++n) _Pragma("unroll") for (int k = 0; k < 2; ++k) dst[n][k] = *(const LAS bf16x8*)(lds + PG8_SB(b, h) + boff + n * 2048 + k * 1024); } while (0)
; #define PG8_MMA(ai, bj, At, Bt) do { __builtin_amdgcn_s_setprio(1); _Pragma("unroll") for (int m = 0; m < 4; ++m) _Pragma("unroll") for (int n = 0; n < 2; ++n) _Pragma("unroll") for (int k = 0; k < 2; ++k) \
;         acc[ai][bj][m][n] = __builtin_amdgcn_mfma_f32_16x16x32_bf16(Bt[n][k], At[m][k], acc[ai][bj][m][n], 0, 0, 0); __builtin_amdgcn_s_setprio(0); } while (0)
; #define PG8_WAIT_V(n) asm volatile("s_waitcnt vmcnt(" #n ")" ::: "memory")
; #define PG8_WAIT_L(n) asm volatile("s_waitcnt lgkmcnt(" #n ")" ::: "memory")
; #define PG8_BAR __builtin_amdgcn_s_barrier()
; #define PG8_SCHED __builtin_amdgcn_sched_barrier(0)
; template <class Epi>
; __device__ __forceinline__ void gemm_phase(LAS unsigned char* lds, const Gemm g, const StaticOrder& S, const Epi& E) {
;     ...
;             PG8_WAIT_L(8); PG8_BAR; PG8_WAIT_L(0); PG8_MMA(0, 0, At, B0); PG8_BAR; PG8_SCHED;
;             PG8_LDB(B1, 1, 1); PG8_STAGE(PG8_SB(1, 0), b3, voffB);
;             PG8_BAR; PG8_WAIT_L(0); PG8_MMA(0, 1, At, B1); PG8_BAR;
;             PG8_LDA(At, 1, 1); PG8_STAGE(PG8_SA(1, 0), a3, voffA);
;             PG8_BAR; PG8_WAIT_L(0); PG8_MMA(1, 0, At, B0); PG8_BAR; PG8_SCHED;
;             PG8_STAGE(PG8_SB(1, 1), b3 + hB, voffB);
;             PG8_WAIT_V(6); PG8_BAR; PG8_MMA(1, 1, At, B1); PG8_BAR;
	s_waitcnt lgkmcnt(0)
	s_setprio 1
	s_waitcnt lgkmcnt(0)
	v_mfma_f32_16x16x32_bf16 v[126:129], v[156:159], v[172:175], v[126:129]
	v_mfma_f32_16x16x32_bf16 v[122:125], v[164:167], v[172:175], v[122:125]
	v_mfma_f32_16x16x32_bf16 v[118:121], v[156:159], v[180:183], v[118:121]
	v_mfma_f32_16x16x32_bf16 v[110:113], v[164:167], v[180:183], v[110:113]
	v_mfma_f32_16x16x32_bf16 v[102:105], v[156:159], v[188:191], v[102:105]
	v_mfma_f32_16x16x32_bf16 v[94:97], v[164:167], v[188:191], v[94:97]
	v_mfma_f32_16x16x32_bf16 v[86:89], v[156:159], v[202:205], v[86:89]
	v_mfma_f32_16x16x32_bf16 v[78:81], v[164:167], v[202:205], v[78:81]
	v_mfma_f32_16x16x32_bf16 v[126:129], v[160:163], v[176:179], v[126:129]
	v_mfma_f32_16x16x32_bf16 v[122:125], v[168:171], v[176:179], v[122:125]
	v_mfma_f32_16x16x32_bf16 v[118:121], v[160:163], v[184:187], v[118:121]
	v_mfma_f32_16x16x32_bf16 v[110:113], v[168:171], v[184:187], v[110:113]
	v_mfma_f32_16x16x32_bf16 v[102:105], v[160:163], v[192:195], v[102:105]
	v_mfma_f32_16x16x32_bf16 v[94:97], v[168:171], v[192:195], v[94:97]
	v_mfma_f32_16x16x32_bf16 v[86:89], v[160:163], v[206:209], v[86:89]
	v_mfma_f32_16x16x32_bf16 v[78:81], v[168:171], v[206:209], v[78:81]
	s_setprio 0
	s_barrier
	s_add_i32 s100, 0, 0x1c000
	s_add_i32 s101, s67, s33
	v_add_u32_e32 v151, s100, v143
	s_add_u32 s68, s48, 0x80
	s_addc_u32 s69, s49, 0
	s_mov_b32 m0, s101
	ds_read_b128 v[210:213], v151
	ds_read_b128 v[214:217], v151 offset:1024
	ds_read_b128 v[218:221], v151 offset:2048
	ds_read_b128 v[222:225], v151 offset:3072
	global_load_lds_dwordx4 v0, s[68:69]
	s_add_i32 m0, s101, 0x2000
	s_nop 0
	global_load_lds_dwordx4 v134, s[68:69]
	s_barrier
	s_waitcnt lgkmcnt(0)
	s_setprio 1
	s_waitcnt lgkmcnt(0)
	v_mfma_f32_16x16x32_bf16 v[114:117], v[210:213], v[172:175], v[114:117]
	v_mfma_f32_16x16x32_bf16 v[106:109], v[218:221], v[172:175], v[106:109]
	v_mfma_f32_16x16x32_bf16 v[98:101], v[210:213], v[180:183], v[98:101]
	v_mfma_f32_16x16x32_bf16 v[90:93], v[218:221], v[180:183], v[90:93]
	v_mfma_f32_16x16x32_bf16 v[82:85], v[210:213], v[188:191], v[82:85]
	v_mfma_f32_16x16x32_bf16 v[74:77], v[218:221], v[188:191], v[74:77]
	v_mfma_f32_16x16x32_bf16 v[70:73], v[210:213], v[202:205], v[70:73]
	v_mfma_f32_16x16x32_bf16 v[66:69], v[218:221], v[202:205], v[66:69]
	v_mfma_f32_16x16x32_bf16 v[114:117], v[214:217], v[176:179], v[114:117]
	v_mfma_f32_16x16x32_bf16 v[106:109], v[222:225], v[176:179], v[106:109]
	v_mfma_f32_16x16x32_bf16 v[98:101], v[214:217], v[184:187], v[98:101]
	v_mfma_f32_16x16x32_bf16 v[90:93], v[222:225], v[184:187], v[90:93]
	v_mfma_f32_16x16x32_bf16 v[82:85], v[214:217], v[192:195], v[82:85]
	v_mfma_f32_16x16x32_bf16 v[74:77], v[222:225], v[192:195], v[74:77]
	v_mfma_f32_16x16x32_bf16 v[70:73], v[214:217], v[206:209], v[70:73]
	v_mfma_f32_16x16x32_bf16 v[66:69], v[222:225], v[206:209], v[66:69]
	s_setprio 0
	s_mov_b32 m0, s58
	s_add_u32 s68, s50, 0x80
	s_addc_u32 s69, s51, 0
	s_barrier
	ds_read_b128 v[172:175], v149 offset:49152
	ds_read_b128 v[176:179], v149 offset:50176
	ds_read_b128 v[180:183], v149 offset:51200
	ds_read_b128 v[184:187], v149 offset:52224
	ds_read_b128 v[188:191], v149 offset:53248
	ds_read_b128 v[192:195], v149 offset:54272
	ds_read_b128 v[202:205], v149 offset:55296
	ds_read_b128 v[206:209], v149 offset:56320
	global_load_lds_dwordx4 v130, s[68:69]
	s_mov_b32 m0, s59
	s_nop 0
	global_load_lds_dwordx4 v132, s[68:69]
	s_barrier
	s_waitcnt lgkmcnt(0)
	s_setprio 1
	s_waitcnt lgkmcnt(0)
	v_mfma_f32_16x16x32_bf16 v[62:65], v[156:159], v[172:175], v[62:65]
	v_mfma_f32_16x16x32_bf16 v[58:61], v[164:167], v[172:175], v[58:61]
	v_mfma_f32_16x16x32_bf16 v[54:57], v[156:159], v[180:183], v[54:57]
	v_mfma_f32_16x16x32_bf16 v[46:49], v[164:167], v[180:183], v[46:49]
	v_mfma_f32_16x16x32_bf16 v[38:41], v[156:159], v[188:191], v[38:41]
	v_mfma_f32_16x16x32_bf16 v[30:33], v[164:167], v[188:191], v[30:33]
	v_mfma_f32_16x16x32_bf16 v[22:25], v[156:159], v[202:205], v[22:25]
	v_mfma_f32_16x16x32_bf16 v[14:17], v[164:167], v[202:205], v[14:17]
	v_mfma_f32_16x16x32_bf16 v[62:65], v[160:163], v[176:179], v[62:65]
	v_mfma_f32_16x16x32_bf16 v[58:61], v[168:171], v[176:179], v[58:61]
	v_mfma_f32_16x16x32_bf16 v[54:57], v[160:163], v[184:187], v[54:57]
	v_mfma_f32_16x16x32_bf16 v[46:49], v[168:171], v[184:187], v[46:49]
	v_mfma_f32_16x16x32_bf16 v[38:41], v[160:163], v[192:195], v[38:41]
	v_mfma_f32_16x16x32_bf16 v[30:33], v[168:171], v[192:195], v[30:33]
	v_mfma_f32_16x16x32_bf16 v[22:25], v[160:163], v[206:209], v[22:25]
	v_mfma_f32_16x16x32_bf16 v[14:17], v[168:171], v[206:209], v[14:17]
	s_setprio 0
	s_barrier
	s_add_u32 s48, s48, 0x40080
	s_addc_u32 s49, s49, 0
	s_add_i32 s100, s100, s33
	s_mov_b32 m0, s100
	s_nop 0
	global_load_lds_dwordx4 v0, s[48:49]
	s_add_i32 m0, s100, 0x2000
	s_nop 0
	global_load_lds_dwordx4 v134, s[48:49]
	s_waitcnt vmcnt(6)
	s_barrier
	s_setprio 1
	v_mfma_f32_16x16x32_bf16 v[50:53], v[210:213], v[172:175], v[50:53]
	v_mfma_f32_16x16x32_bf16 v[42:45], v[218:221], v[172:175], v[42:45]
	v_mfma_f32_16x16x32_bf16 v[34:37], v[210:213], v[180:183], v[34:37]
	v_mfma_f32_16x16x32_bf16 v[26:29], v[218:221], v[180:183], v[26:29]
	v_mfma_f32_16x16x32_bf16 v[18:21], v[210:213], v[188:191], v[18:21]
	v_mfma_f32_16x16x32_bf16 v[10:13], v[218:221], v[188:191], v[10:13]
	v_mfma_f32_16x16x32_bf16 v[6:9], v[210:213], v[202:205], v[6:9]
	v_mfma_f32_16x16x32_bf16 v[2:5], v[218:221], v[202:205], v[2:5]
	v_mfma_f32_16x16x32_bf16 v[50:53], v[214:217], v[176:179], v[50:53]
	v_mfma_f32_16x16x32_bf16 v[42:45], v[222:225], v[176:179], v[42:45]
	v_mfma_f32_16x16x32_bf16 v[34:37], v[214:217], v[184:187], v[34:37]
	v_mfma_f32_16x16x32_bf16 v[26:29], v[222:225], v[184:187], v[26:29]
	v_mfma_f32_16x16x32_bf16 v[18:21], v[214:217], v[192:195], v[18:21]
	v_mfma_f32_16x16x32_bf16 v[10:13], v[222:225], v[192:195], v[10:13]
	v_mfma_f32_16x16x32_bf16 v[6:9], v[214:217], v[206:209], v[6:9]
	v_mfma_f32_16x16x32_bf16 v[2:5], v[222:225], v[206:209], v[2:5]
	s_setprio 0
	s_add_i32 s66, s66, 2
	s_add_u32 s46, s46, 0x100
	s_addc_u32 s47, s47, 0
	s_add_u32 s64, s64, 0x100
	s_addc_u32 s65, s65, 0
	s_cmp_gt_u32 s66, 13
	s_barrier
; __device__ __forceinline__ u32x4 pack8(const f32x4 a, const f32x4 b) { u32x4 w; w.x = cvt_pk_bf16(a[0], a[1]); w.y = cvt_pk_bf16(a[2], a[3]); w.z = cvt_pk_bf16(b[0], b[1]); w.w = cvt_pk_bf16(b[2], b[3]); return w; }
;     __device__ __forceinline__ void operator()(const Acc& acc, const Unit& u, int wr, int wc, int fr, int fq, const RsPre& pr) const {
;         asm volatile("" : "+v"(fr), "+v"(fq));
;         const int row0 = u.pm * 256 + wr * 64 + fr, col0 = u.pn * 256 + wc * 32 + 8 * fq;
;         const float (&rs)[2][4] = pr.rs;
; #pragma unroll
;         for (int ai = 0; ai < 2; ++ai)
; #pragma unroll
;             for (int m = 0; m < 4; ++m) { bf16_t* rowp = O + (size_t)(row0 + ai * 128 + m * 16) * ldc + col0;
; #pragma unroll
;                 for (int bj = 0; bj < 2; ++bj) *(u32x4*)(rowp + bj * 128) = pack8(acc[ai][bj][m][0] * rs[ai][m], acc[ai][bj][m][1] * rs[ai][m]); }
;     }
	s_cbranch_scc0 .LBB0_623
	v_mov_b32_e32 v151, v137
	v_mov_b32_e32 v153, v139
	s_lshl_b32 s15, s44, 8
	s_add_i32 s15, s15, s52
	v_add_u32_e32 v151, s15, v151
	s_lshl_b32 s15, s45, 8
	s_or_b32 s15, s15, s57
	v_lshl_add_u32 v158, v153, 3, s15
	v_lshlrev_b32_e32 v158, 1, v158
	v_mad_u32_u24 v160, v151, s96, v158
	s_waitcnt vmcnt(0)
	v_pk_mul_f32 v[128:129], v[154:155], v[128:129] op_sel_hi:[0,1]
	v_pk_mul_f32 v[126:127], v[154:155], v[126:127] op_sel_hi:[0,1]
	v_pk_mul_f32 v[162:163], v[154:155], v[124:125] op_sel_hi:[0,1]
	v_pk_mul_f32 v[124:125], v[154:155], v[122:123] op_sel_hi:[0,1]
	v_cvt_pk_bf16_f32 v122, v126, v127
	v_cvt_pk_bf16_f32 v123, v128, v129
	v_cvt_pk_bf16_f32 v124, v124, v125
	v_cvt_pk_bf16_f32 v125, v162, v163
	global_store_dwordx4 v160, v[122:125], s[20:21]
	v_pk_mul_f32 v[116:117], v[154:155], v[116:117] op_sel_hi:[0,1]
	v_pk_mul_f32 v[114:115], v[154:155], v[114:115] op_sel_hi:[0,1]
	v_pk_mul_f32 v[122:123], v[154:155], v[108:109] op_sel_hi:[0,1]
	v_pk_mul_f32 v[108:109], v[154:155], v[106:107] op_sel_hi:[0,1]
	v_cvt_pk_bf16_f32 v106, v114, v115
	v_cvt_pk_bf16_f32 v107, v116, v117
	v_cvt_pk_bf16_f32 v108, v108, v109
	v_cvt_pk_bf16_f32 v109, v122, v123
	global_store_dwordx4 v160, v[106:109], s[20:21] offset:256
	v_pk_mul_f32 v[112:113], v[152:153], v[112:113] op_sel_hi:[0,1]
	v_pk_mul_f32 v[110:111], v[152:153], v[110:111] op_sel_hi:[0,1]
	v_add_u32_e32 v114, 0x22000, v160
	v_pk_mul_f32 v[108:109], v[152:153], v[120:121] op_sel_hi:[0,1]
	v_pk_mul_f32 v[106:107], v[152:153], v[118:119] op_sel_hi:[0,1]
	v_cvt_pk_bf16_f32 v106, v106, v107
	v_cvt_pk_bf16_f32 v107, v108, v109
	v_cvt_pk_bf16_f32 v108, v110, v111
	v_cvt_pk_bf16_f32 v109, v112, v113
	global_store_dwordx4 v114, v[106:109], s[20:21]
	v_pk_mul_f32 v[100:101], v[152:153], v[100:101] op_sel_hi:[0,1]
	v_pk_mul_f32 v[98:99], v[152:153], v[98:99] op_sel_hi:[0,1]
	v_pk_mul_f32 v[106:107], v[152:153], v[92:93] op_sel_hi:[0,1]
	v_pk_mul_f32 v[92:93], v[152:153], v[90:91] op_sel_hi:[0,1]
	v_cvt_pk_bf16_f32 v90, v98, v99
	v_cvt_pk_bf16_f32 v91, v100, v101
	v_cvt_pk_bf16_f32 v92, v92, v93
	v_cvt_pk_bf16_f32 v93, v106, v107
	global_store_dwordx4 v114, v[90:93], s[20:21] offset:256
	v_pk_mul_f32 v[96:97], v[150:151], v[96:97] op_sel_hi:[0,1]
	v_pk_mul_f32 v[94:95], v[150:151], v[94:95] op_sel_hi:[0,1]
	v_add_u32_e32 v98, 0x44000, v160
	v_pk_mul_f32 v[92:93], v[150:151], v[104:105] op_sel_hi:[0,1]
	v_pk_mul_f32 v[90:91], v[150:151], v[102:103] op_sel_hi:[0,1]
	v_cvt_pk_bf16_f32 v90, v90, v91
	v_cvt_pk_bf16_f32 v91, v92, v93
	v_cvt_pk_bf16_f32 v92, v94, v95
	v_cvt_pk_bf16_f32 v93, v96, v97
	global_store_dwordx4 v98, v[90:93], s[20:21]
	v_pk_mul_f32 v[84:85], v[150:151], v[84:85] op_sel_hi:[0,1]
	v_pk_mul_f32 v[82:83], v[150:151], v[82:83] op_sel_hi:[0,1]
	v_pk_mul_f32 v[90:91], v[150:151], v[76:77] op_sel_hi:[0,1]
	v_pk_mul_f32 v[76:77], v[150:151], v[74:75] op_sel_hi:[0,1]
	v_cvt_pk_bf16_f32 v74, v82, v83
	v_cvt_pk_bf16_f32 v75, v84, v85
	v_cvt_pk_bf16_f32 v76, v76, v77
	v_cvt_pk_bf16_f32 v77, v90, v91
	global_store_dwordx4 v98, v[74:77], s[20:21] offset:256
	v_pk_mul_f32 v[80:81], v[148:149], v[80:81] op_sel_hi:[0,1]
	v_pk_mul_f32 v[78:79], v[148:149], v[78:79] op_sel_hi:[0,1]
	v_add_u32_e32 v82, 0x66000, v160
	v_pk_mul_f32 v[76:77], v[148:149], v[88:89] op_sel_hi:[0,1]
	v_pk_mul_f32 v[74:75], v[148:149], v[86:87] op_sel_hi:[0,1]
	v_cvt_pk_bf16_f32 v74, v74, v75
	v_cvt_pk_bf16_f32 v75, v76, v77
	v_cvt_pk_bf16_f32 v76, v78, v79
	v_cvt_pk_bf16_f32 v77, v80, v81
	global_store_dwordx4 v82, v[74:77], s[20:21]
	v_pk_mul_f32 v[72:73], v[148:149], v[72:73] op_sel_hi:[0,1]
	v_pk_mul_f32 v[70:71], v[148:149], v[70:71] op_sel_hi:[0,1]
	v_pk_mul_f32 v[74:75], v[148:149], v[68:69] op_sel_hi:[0,1]
	v_pk_mul_f32 v[68:69], v[148:149], v[66:67] op_sel_hi:[0,1]
	v_cvt_pk_bf16_f32 v66, v70, v71
	v_cvt_pk_bf16_f32 v67, v72, v73
	v_cvt_pk_bf16_f32 v68, v68, v69
	v_cvt_pk_bf16_f32 v69, v74, v75
	global_store_dwordx4 v82, v[66:69], s[20:21] offset:256
	v_pk_mul_f32 v[64:65], v[142:143], v[64:65] op_sel_hi:[0,1]
	v_pk_mul_f32 v[62:63], v[142:143], v[62:63] op_sel_hi:[0,1]
	v_pk_mul_f32 v[68:69], v[142:143], v[60:61] op_sel_hi:[0,1]
	v_pk_mul_f32 v[60:61], v[142:143], v[58:59] op_sel_hi:[0,1]
	v_add_u32_e32 v66, 0x110000, v160
	v_cvt_pk_bf16_f32 v58, v62, v63
	v_cvt_pk_bf16_f32 v59, v64, v65
	v_cvt_pk_bf16_f32 v60, v60, v61
	v_cvt_pk_bf16_f32 v61, v68, v69
	global_store_dwordx4 v66, v[58:61], s[20:21]
	v_pk_mul_f32 v[52:53], v[142:143], v[52:53] op_sel_hi:[0,1]
	v_pk_mul_f32 v[50:51], v[142:143], v[50:51] op_sel_hi:[0,1]
	v_pk_mul_f32 v[58:59], v[142:143], v[44:45] op_sel_hi:[0,1]
	v_pk_mul_f32 v[44:45], v[142:143], v[42:43] op_sel_hi:[0,1]
	v_cvt_pk_bf16_f32 v42, v50, v51
	v_cvt_pk_bf16_f32 v43, v52, v53
	v_cvt_pk_bf16_f32 v44, v44, v45
	v_cvt_pk_bf16_f32 v45, v58, v59
	global_store_dwordx4 v66, v[42:45], s[20:21] offset:256
	v_pk_mul_f32 v[48:49], v[140:141], v[48:49] op_sel_hi:[0,1]
	v_pk_mul_f32 v[46:47], v[140:141], v[46:47] op_sel_hi:[0,1]
	v_add_u32_e32 v50, 0x132000, v160
	v_pk_mul_f32 v[44:45], v[140:141], v[56:57] op_sel_hi:[0,1]
	v_pk_mul_f32 v[42:43], v[140:141], v[54:55] op_sel_hi:[0,1]
	v_cvt_pk_bf16_f32 v42, v42, v43
	v_cvt_pk_bf16_f32 v43, v44, v45
	v_cvt_pk_bf16_f32 v44, v46, v47
	v_cvt_pk_bf16_f32 v45, v48, v49
	global_store_dwordx4 v50, v[42:45], s[20:21]
	v_pk_mul_f32 v[36:37], v[140:141], v[36:37] op_sel_hi:[0,1]
	v_pk_mul_f32 v[34:35], v[140:141], v[34:35] op_sel_hi:[0,1]
; __device__ __forceinline__ u32x4 pack8(const f32x4 a, const f32x4 b) { u32x4 w; w.x = cvt_pk_bf16(a[0], a[1]); w.y = cvt_pk_bf16(a[2], a[3]); w.z = cvt_pk_bf16(b[0], b[1]); w.w = cvt_pk_bf16(b[2], b[3]); return w; }
; template <class Epi>
; __device__ __forceinline__ void gemm_phase(LAS unsigned char* lds, const Gemm g, const StaticOrder& S, const Epi& E) {
;     ...
;         if (!(Epi::PAIRS && cur.alt == 0)) {
; #pragma unroll
;         for (int a = 0; a < 2; ++a)
; #pragma unroll
;             for (int b = 0; b < 2; ++b)
; #pragma unroll
;                 for (int m = 0; m < 4; ++m)
; #pragma unroll
;                     for (int n = 0; n < 2; ++n) acc[a][b][m][n] = (f32x4){0.f, 0.f, 0.f, 0.f}; }
;     __device__ __forceinline__ void operator()(const Acc& acc, const Unit& u, int wr, int wc, int fr, int fq, const RsPre& pr) const {
;         asm volatile("" : "+v"(fr), "+v"(fq));
;         const int row0 = u.pm * 256 + wr * 64 + fr, col0 = u.pn * 256 + wc * 32 + 8 * fq;
;         const float (&rs)[2][4] = pr.rs;
; #pragma unroll
;         for (int ai = 0; ai < 2; ++ai)
; #pragma unroll
;             for (int m = 0; m < 4; ++m) { bf16_t* rowp = O + (size_t)(row0 + ai * 128 + m * 16) * ldc + col0;
; #pragma unroll
;                 for (int bj = 0; bj < 2; ++bj) *(u32x4*)(rowp + bj * 128) = pack8(acc[ai][bj][m][0] * rs[ai][m], acc[ai][bj][m][1] * rs[ai][m]); }
;     }
	v_pk_mul_f32 v[42:43], v[140:141], v[28:29] op_sel_hi:[0,1]
	v_pk_mul_f32 v[28:29], v[140:141], v[26:27] op_sel_hi:[0,1]
	v_cvt_pk_bf16_f32 v26, v34, v35
	v_cvt_pk_bf16_f32 v27, v36, v37
	v_cvt_pk_bf16_f32 v28, v28, v29
	v_cvt_pk_bf16_f32 v29, v42, v43
	global_store_dwordx4 v50, v[26:29], s[20:21] offset:256
	v_pk_mul_f32 v[32:33], v[138:139], v[32:33] op_sel_hi:[0,1]
	v_pk_mul_f32 v[30:31], v[138:139], v[30:31] op_sel_hi:[0,1]
	v_add_u32_e32 v34, 0x154000, v160
	v_pk_mul_f32 v[28:29], v[138:139], v[40:41] op_sel_hi:[0,1]
	v_pk_mul_f32 v[26:27], v[138:139], v[38:39] op_sel_hi:[0,1]
	v_cvt_pk_bf16_f32 v26, v26, v27
	v_cvt_pk_bf16_f32 v27, v28, v29
	v_cvt_pk_bf16_f32 v28, v30, v31
	v_cvt_pk_bf16_f32 v29, v32, v33
	global_store_dwordx4 v34, v[26:29], s[20:21]
	v_pk_mul_f32 v[20:21], v[138:139], v[20:21] op_sel_hi:[0,1]
	v_pk_mul_f32 v[18:19], v[138:139], v[18:19] op_sel_hi:[0,1]
	v_pk_mul_f32 v[26:27], v[138:139], v[12:13] op_sel_hi:[0,1]
	v_pk_mul_f32 v[12:13], v[138:139], v[10:11] op_sel_hi:[0,1]
	v_cvt_pk_bf16_f32 v10, v18, v19
	v_cvt_pk_bf16_f32 v11, v20, v21
	v_cvt_pk_bf16_f32 v12, v12, v13
	v_cvt_pk_bf16_f32 v13, v26, v27
	global_store_dwordx4 v34, v[10:13], s[20:21] offset:256
	v_pk_mul_f32 v[16:17], v[136:137], v[16:17] op_sel_hi:[0,1]
	v_pk_mul_f32 v[14:15], v[136:137], v[14:15] op_sel_hi:[0,1]
	v_add_u32_e32 v18, 0x176000, v160
	v_pk_mul_f32 v[12:13], v[136:137], v[24:25] op_sel_hi:[0,1]
	v_pk_mul_f32 v[10:11], v[136:137], v[22:23] op_sel_hi:[0,1]
	v_cvt_pk_bf16_f32 v10, v10, v11
	v_cvt_pk_bf16_f32 v11, v12, v13
	v_cvt_pk_bf16_f32 v12, v14, v15
	v_cvt_pk_bf16_f32 v13, v16, v17
	global_store_dwordx4 v18, v[10:13], s[20:21]
	v_pk_mul_f32 v[8:9], v[136:137], v[8:9] op_sel_hi:[0,1]
	v_pk_mul_f32 v[6:7], v[136:137], v[6:7] op_sel_hi:[0,1]
	v_pk_mul_f32 v[10:11], v[136:137], v[4:5] op_sel_hi:[0,1]
	v_pk_mul_f32 v[4:5], v[136:137], v[2:3] op_sel_hi:[0,1]
	v_cvt_pk_bf16_f32 v2, v6, v7
	v_cvt_pk_bf16_f32 v3, v8, v9
	v_cvt_pk_bf16_f32 v4, v4, v5
	v_cvt_pk_bf16_f32 v5, v10, v11
	s_mov_b64 s[44:45], -1
	s_and_b64 vcc, vcc, exec
	v_mov_b32_e32 v6, 0
	v_mov_b32_e32 v7, 0
	v_mov_b32_e32 v8, 0
	v_mov_b32_e32 v9, 0
	v_mov_b32_e32 v10, 0
	v_mov_b32_e32 v11, 0
	v_mov_b32_e32 v12, 0
	v_mov_b32_e32 v13, 0
	v_mov_b32_e32 v19, 0
	v_mov_b32_e32 v20, 0
	v_mov_b32_e32 v21, 0
	v_mov_b32_e32 v26, 0
	v_mov_b32_e32 v27, 0
	v_mov_b32_e32 v28, 0
	v_mov_b32_e32 v29, 0
	v_mov_b32_e32 v34, 0
	v_mov_b32_e32 v35, 0
	v_mov_b32_e32 v36, 0
	v_mov_b32_e32 v37, 0
	v_mov_b32_e32 v42, 0
	v_mov_b32_e32 v43, 0
	v_mov_b32_e32 v44, 0
	v_mov_b32_e32 v45, 0
	v_mov_b32_e32 v50, 0
	v_mov_b32_e32 v51, 0
	v_mov_b32_e32 v52, 0
	v_mov_b32_e32 v53, 0
	v_mov_b32_e32 v14, 0
	v_mov_b32_e32 v15, 0
	v_mov_b32_e32 v16, 0
	v_mov_b32_e32 v17, 0
	v_mov_b32_e32 v22, 0
	v_mov_b32_e32 v23, 0
	v_mov_b32_e32 v24, 0
	v_mov_b32_e32 v25, 0
	v_mov_b32_e32 v30, 0
	v_mov_b32_e32 v31, 0
	v_mov_b32_e32 v32, 0
	v_mov_b32_e32 v33, 0
	v_mov_b32_e32 v38, 0
	v_mov_b32_e32 v39, 0
	v_mov_b32_e32 v40, 0
	v_mov_b32_e32 v41, 0
	v_mov_b32_e32 v46, 0
	v_mov_b32_e32 v47, 0
	v_mov_b32_e32 v48, 0
	v_mov_b32_e32 v49, 0
	v_mov_b32_e32 v54, 0
	v_mov_b32_e32 v55, 0
	v_mov_b32_e32 v56, 0
	v_mov_b32_e32 v57, 0
	v_mov_b32_e32 v58, 0
	v_mov_b32_e32 v59, 0
	v_mov_b32_e32 v60, 0
	v_mov_b32_e32 v61, 0
	v_mov_b32_e32 v62, 0
	v_mov_b32_e32 v63, 0
	v_mov_b32_e32 v64, 0
	v_mov_b32_e32 v65, 0
	v_mov_b32_e32 v66, 0
	v_mov_b32_e32 v67, 0
	v_mov_b32_e32 v68, 0
	v_mov_b32_e32 v69, 0
	v_mov_b32_e32 v70, 0
	v_mov_b32_e32 v71, 0
	v_mov_b32_e32 v72, 0
	v_mov_b32_e32 v73, 0
	v_mov_b32_e32 v74, 0
	v_mov_b32_e32 v75, 0
	v_mov_b32_e32 v76, 0
	v_mov_b32_e32 v77, 0
	v_mov_b32_e32 v82, 0
	v_mov_b32_e32 v83, 0
	v_mov_b32_e32 v84, 0
	v_mov_b32_e32 v85, 0
	v_mov_b32_e32 v90, 0
	v_mov_b32_e32 v91, 0
	v_mov_b32_e32 v92, 0
	v_mov_b32_e32 v93, 0
	v_mov_b32_e32 v98, 0
	v_mov_b32_e32 v99, 0
	v_mov_b32_e32 v100, 0
	v_mov_b32_e32 v101, 0
	v_mov_b32_e32 v106, 0
	v_mov_b32_e32 v107, 0
	v_mov_b32_e32 v108, 0
	v_mov_b32_e32 v109, 0
	v_mov_b32_e32 v114, 0
	v_mov_b32_e32 v115, 0
	v_mov_b32_e32 v116, 0
	v_mov_b32_e32 v117, 0
	v_mov_b32_e32 v78, 0
	v_mov_b32_e32 v79, 0
	v_mov_b32_e32 v80, 0
	v_mov_b32_e32 v81, 0
	v_mov_b32_e32 v86, 0
	v_mov_b32_e32 v87, 0
	v_mov_b32_e32 v88, 0
	v_mov_b32_e32 v89, 0
	v_mov_b32_e32 v94, 0
	v_mov_b32_e32 v95, 0
	v_mov_b32_e32 v96, 0
	v_mov_b32_e32 v97, 0
	v_mov_b32_e32 v102, 0
	v_mov_b32_e32 v103, 0
	v_mov_b32_e32 v104, 0
	v_mov_b32_e32 v105, 0
	v_mov_b32_e32 v110, 0
	v_mov_b32_e32 v111, 0
	v_mov_b32_e32 v112, 0
	v_mov_b32_e32 v113, 0
	v_mov_b32_e32 v118, 0
	v_mov_b32_e32 v119, 0
	v_mov_b32_e32 v120, 0
	v_mov_b32_e32 v121, 0
	v_mov_b32_e32 v122, 0
	v_mov_b32_e32 v123, 0
	v_mov_b32_e32 v124, 0
	v_mov_b32_e32 v125, 0
	v_mov_b32_e32 v126, 0
	v_mov_b32_e32 v127, 0
	v_mov_b32_e32 v128, 0
	v_mov_b32_e32 v129, 0
	global_store_dwordx4 v18, v[2:5], s[20:21] offset:256
	s_cbranch_vccz .LBB0_615
	s_nop 0
	v_lshl_add_u32 v2, s22, 8, v141
	v_ashrrev_i32_e32 v3, 31, v2
	v_lshl_add_u64 v[2:3], v[2:3], 2, s[10:11]
	global_load_dword v154, v[2:3], off
	global_load_dword v152, v[2:3], off offset:64
	global_load_dword v150, v[2:3], off offset:128
	global_load_dword v148, v[2:3], off offset:192
	global_load_dword v142, v[2:3], off offset:512
	global_load_dword v140, v[2:3], off offset:576
	global_load_dword v138, v[2:3], off offset:640
	global_load_dword v136, v[2:3], off offset:704
	s_mov_b64 s[44:45], 0
	s_branch .LBB0_615
